# P10 hand-written v2: four divisions / conv chains of a row interleaved
# speedup vs baseline: 1.0062x; 1.0060x over previous
.LBB0_1005:
	s_cmp_lt_i32 s34, 11
	s_cselect_b64 s[10:11], -1, 0
	s_and_b64 s[6:7], s[10:11], s[6:7]
	s_andn2_b64 vcc, exec, s[6:7]
	s_cbranch_vccnz .LBB0_1012
	v_lshl_or_b32 v1, s2, 9, v0
	s_waitcnt lgkmcnt(0)
	s_mov_b32 s3, 0x160000
	v_cmp_gt_i32_e32 vcc, s3, v1
	s_and_saveexec_b64 s[12:13], vcc
	s_cbranch_execz .LBB0_1011
	s_load_dword s3, s[0:1], 0xd8
	s_add_u32 s14, s70, 0x7900000
	s_addc_u32 s15, s71, 0
	s_add_u32 s16, s14, 0x2c00
	s_addc_u32 s17, s15, 0
	s_add_u32 s18, s70, 0x1600000
	s_addc_u32 s19, s71, 0
	s_mov_b32 s38, 0x2e8ba2e9
	s_mov_b32 s39, 0x160000
	s_waitcnt lgkmcnt(0)
	s_lshl_b32 s3, s3, 9
	s_mov_b64 s[6:7], exec
	v_mov_b32_e32 v216, 0
	v_mov_b32_e32 v154, v1
	v_mul_hi_u32 v2, v154, s38
	v_lshrrev_b32_e32 v2, 8, v2
	v_mul_u32_u24_e32 v3, 0x580, v2
	v_sub_u32_e32 v3, v154, v3
	v_lshlrev_b32_e32 v4, 3, v3
	v_and_b32_e32 v5, 0x1ff, v2
	v_cmp_eq_u32_e32 vcc, 0, v5
	s_nop 1
	v_cndmask_b32_e64 v153, 0, 1, vcc
	v_lshlrev_b32_e32 v5, 3, v2
	v_mul_u32_u24_e32 v6, 0x2c00, v5
	v_add_u32_e32 v152, v6, v4
	v_mul_u32_u24_e32 v6, 0x5800, v5
	v_add_u32_e32 v6, v6, v4
	v_add_u32_e32 v7, 0xffff5000, v6
	v_cndmask_b32_e32 v7, v7, v6, vcc
	global_load_dwordx2 v[8:9], v7, s[14:15]
	global_load_dwordx2 v[28:29], v7, s[16:17]
	v_add_u32_e32 v7, 0xffffa800, v6
	v_cndmask_b32_e32 v7, v7, v6, vcc
	global_load_dwordx2 v[10:11], v7, s[14:15]
	global_load_dwordx2 v[30:31], v7, s[16:17]
	global_load_dwordx2 v[12:13], v6, s[14:15]
	global_load_dwordx2 v[32:33], v6, s[16:17]
	v_add_u32_e32 v6, 0x5800, v6
	global_load_dwordx2 v[14:15], v6, s[14:15]
	global_load_dwordx2 v[34:35], v6, s[16:17]
	v_add_u32_e32 v6, 0x5800, v6
	global_load_dwordx2 v[16:17], v6, s[14:15]
	global_load_dwordx2 v[36:37], v6, s[16:17]
	v_add_u32_e32 v6, 0x5800, v6
	global_load_dwordx2 v[18:19], v6, s[14:15]
	global_load_dwordx2 v[38:39], v6, s[16:17]
	v_add_u32_e32 v6, 0x5800, v6
	global_load_dwordx2 v[20:21], v6, s[14:15]
	global_load_dwordx2 v[40:41], v6, s[16:17]
	v_add_u32_e32 v6, 0x5800, v6
	global_load_dwordx2 v[22:23], v6, s[14:15]
	global_load_dwordx2 v[42:43], v6, s[16:17]
	v_add_u32_e32 v6, 0x5800, v6
	global_load_dwordx2 v[24:25], v6, s[14:15]
	global_load_dwordx2 v[44:45], v6, s[16:17]
	v_add_u32_e32 v6, 0x5800, v6
	global_load_dwordx2 v[26:27], v6, s[14:15]
	global_load_dwordx2 v[46:47], v6, s[16:17]
	v_lshlrev_b32_e32 v4, 4, v3
	v_add_u32_e32 v5, 0xb000, v4
	global_load_dwordx4 v[48:51], v5, s[54:55]
	global_load_dwordx4 v[52:55], v4, s[54:55]
	v_add_u32_e32 v5, 0x16000, v4
	global_load_dwordx4 v[56:59], v5, s[54:55]
	global_load_dwordx4 v[60:63], v4, s[56:57]
	v_add_u32_e32 v5, 0x10800, v4
	global_load_dwordx4 v[64:67], v5, s[54:55]
	v_add_u32_e32 v5, 0x5800, v4
	global_load_dwordx4 v[68:71], v5, s[54:55]
	v_add_u32_e32 v5, 0x1b800, v4
	global_load_dwordx4 v[72:75], v5, s[54:55]
	v_add_u32_e32 v5, 0x5800, v4
	global_load_dwordx4 v[76:79], v5, s[56:57]
	global_store_dwordx2 v152, v[216:217], s[18:19]
	v_add_u32_e32 v152, 0x2c00, v152
	global_store_dwordx2 v152, v[216:217], s[18:19]
	v_add_u32_e32 v152, 0x2c00, v152
	global_store_dwordx2 v152, v[216:217], s[18:19]
	v_add_u32_e32 v152, 0x2c00, v152
	global_store_dwordx2 v152, v[216:217], s[18:19]
	v_add_u32_e32 v152, 0x2c00, v152
	global_store_dwordx2 v152, v[216:217], s[18:19]
	v_add_u32_e32 v152, 0x2c00, v152
	global_store_dwordx2 v152, v[216:217], s[18:19]
	v_add_u32_e32 v152, 0x2c00, v152
	global_store_dwordx2 v152, v[216:217], s[18:19]
	v_add_u32_e32 v152, 0x2c00, v152
	global_store_dwordx2 v152, v[216:217], s[18:19]
	v_add_u32_e32 v152, 0xfffecc00, v152
	v_mov_b32_e32 v217, 0
.Lcv_loop:
	v_add_u32_e32 v158, s3, v154
	v_cmp_gt_u32_e32 vcc, s39, v158
	s_and_b64 s[8:9], vcc, exec
	s_nop 0
	v_cndmask_b32_e32 v218, v154, v158, vcc
	v_mul_hi_u32 v2, v218, s38
	v_lshrrev_b32_e32 v2, 8, v2
	v_mul_u32_u24_e32 v3, 0x580, v2
	v_sub_u32_e32 v3, v218, v3
	v_lshlrev_b32_e32 v4, 3, v3
	v_and_b32_e32 v5, 0x1ff, v2
	v_cmp_eq_u32_e32 vcc, 0, v5
	s_nop 1
	v_cndmask_b32_e64 v157, 0, 1, vcc
	v_lshlrev_b32_e32 v5, 3, v2
	v_mul_u32_u24_e32 v6, 0x2c00, v5
	v_add_u32_e32 v156, v6, v4
	v_mul_u32_u24_e32 v6, 0x5800, v5
	v_add_u32_e32 v6, v6, v4
	v_add_u32_e32 v7, 0xffff5000, v6
	v_cndmask_b32_e32 v7, v7, v6, vcc
	global_load_dwordx2 v[80:81], v7, s[14:15]
	global_load_dwordx2 v[100:101], v7, s[16:17]
	v_add_u32_e32 v7, 0xffffa800, v6
	v_cndmask_b32_e32 v7, v7, v6, vcc
	global_load_dwordx2 v[82:83], v7, s[14:15]
	global_load_dwordx2 v[102:103], v7, s[16:17]
	global_load_dwordx2 v[84:85], v6, s[14:15]
	global_load_dwordx2 v[104:105], v6, s[16:17]
	v_add_u32_e32 v6, 0x5800, v6
	global_load_dwordx2 v[86:87], v6, s[14:15]
	global_load_dwordx2 v[106:107], v6, s[16:17]
	v_add_u32_e32 v6, 0x5800, v6
	global_load_dwordx2 v[88:89], v6, s[14:15]
	global_load_dwordx2 v[108:109], v6, s[16:17]
	v_add_u32_e32 v6, 0x5800, v6
	global_load_dwordx2 v[90:91], v6, s[14:15]
	global_load_dwordx2 v[110:111], v6, s[16:17]
	v_add_u32_e32 v6, 0x5800, v6
	global_load_dwordx2 v[92:93], v6, s[14:15]
	global_load_dwordx2 v[112:113], v6, s[16:17]
	v_add_u32_e32 v6, 0x5800, v6
	global_load_dwordx2 v[94:95], v6, s[14:15]
	global_load_dwordx2 v[114:115], v6, s[16:17]
	v_add_u32_e32 v6, 0x5800, v6
	global_load_dwordx2 v[96:97], v6, s[14:15]
	global_load_dwordx2 v[116:117], v6, s[16:17]
	v_add_u32_e32 v6, 0x5800, v6
	global_load_dwordx2 v[98:99], v6, s[14:15]
	global_load_dwordx2 v[118:119], v6, s[16:17]
	v_lshlrev_b32_e32 v4, 4, v3
	v_add_u32_e32 v5, 0xb000, v4
	global_load_dwordx4 v[120:123], v5, s[54:55]
	global_load_dwordx4 v[124:127], v4, s[54:55]
	v_add_u32_e32 v5, 0x16000, v4
	global_load_dwordx4 v[128:131], v5, s[54:55]
	global_load_dwordx4 v[132:135], v4, s[56:57]
	v_add_u32_e32 v5, 0x10800, v4
	global_load_dwordx4 v[136:139], v5, s[54:55]
	v_add_u32_e32 v5, 0x5800, v4
	global_load_dwordx4 v[140:143], v5, s[54:55]
	v_add_u32_e32 v5, 0x1b800, v4
	global_load_dwordx4 v[144:147], v5, s[54:55]
	v_add_u32_e32 v5, 0x5800, v4
	global_load_dwordx4 v[148:151], v5, s[56:57]
	s_mov_b64 s[38:39], s[8:9]
	s_waitcnt vmcnt(36)
	v_cmp_ne_u32_e32 vcc, 0, v153
	s_nop 1
	v_cndmask_b32_e32 v8, v8, v216, vcc
	v_cndmask_b32_e32 v9, v9, v216, vcc
	v_cndmask_b32_e32 v10, v10, v216, vcc
	v_cndmask_b32_e32 v11, v11, v216, vcc
	v_cndmask_b32_e32 v28, v28, v216, vcc
	v_cndmask_b32_e32 v29, v29, v216, vcc
	v_cndmask_b32_e32 v30, v30, v216, vcc
	v_cndmask_b32_e32 v31, v31, v216, vcc
	v_lshlrev_b32_e32 v160, 16, v8
	v_and_b32_e32 v161, 0xffff0000, v8
	v_lshlrev_b32_e32 v162, 16, v9
	v_and_b32_e32 v163, 0xffff0000, v9
	v_lshlrev_b32_e32 v172, 16, v28
	v_and_b32_e32 v173, 0xffff0000, v28
	v_lshlrev_b32_e32 v174, 16, v29
	v_and_b32_e32 v175, 0xffff0000, v29
	v_lshlrev_b32_e32 v164, 16, v10
	v_and_b32_e32 v165, 0xffff0000, v10
	v_lshlrev_b32_e32 v166, 16, v11
	v_and_b32_e32 v167, 0xffff0000, v11
	v_lshlrev_b32_e32 v176, 16, v30
	v_and_b32_e32 v177, 0xffff0000, v30
	v_lshlrev_b32_e32 v178, 16, v31
	v_and_b32_e32 v179, 0xffff0000, v31
	v_lshlrev_b32_e32 v168, 16, v12
	v_and_b32_e32 v169, 0xffff0000, v12
	v_lshlrev_b32_e32 v170, 16, v13
	v_and_b32_e32 v171, 0xffff0000, v13
	v_lshlrev_b32_e32 v180, 16, v32
	v_and_b32_e32 v181, 0xffff0000, v32
	v_lshlrev_b32_e32 v182, 16, v33
	v_and_b32_e32 v183, 0xffff0000, v33
	v_pk_mul_f32 v[184:185], v[48:49], v[164:165]
	v_pk_mul_f32 v[188:189], v[64:65], v[176:177]
	v_pk_mul_f32 v[186:187], v[50:51], v[166:167]
	v_pk_mul_f32 v[190:191], v[66:67], v[178:179]
	v_pk_fma_f32 v[184:185], v[52:53], v[160:161], v[184:185]
	v_pk_fma_f32 v[188:189], v[68:69], v[172:173], v[188:189]
	v_pk_fma_f32 v[186:187], v[54:55], v[162:163], v[186:187]
	v_pk_fma_f32 v[190:191], v[70:71], v[174:175], v[190:191]
	v_pk_fma_f32 v[184:185], v[56:57], v[168:169], v[184:185]
	v_pk_fma_f32 v[188:189], v[72:73], v[180:181], v[188:189]
	v_pk_fma_f32 v[186:187], v[58:59], v[170:171], v[186:187]
	v_pk_fma_f32 v[190:191], v[74:75], v[182:183], v[190:191]
	v_pk_add_f32 v[184:185], v[184:185], v[60:61]
	v_pk_add_f32 v[188:189], v[188:189], v[76:77]
	v_pk_add_f32 v[186:187], v[186:187], v[62:63]
	v_pk_add_f32 v[190:191], v[190:191], v[78:79]
	v_mul_f32_e32 v192, 0xbfb8aa3b, v188
	v_mul_f32_e32 v193, 0xbfb8aa3b, v189
	v_mul_f32_e32 v194, 0xbfb8aa3b, v190
	v_mul_f32_e32 v195, 0xbfb8aa3b, v191
	v_exp_f32_e32 v192, v192
	v_exp_f32_e32 v193, v193
	v_exp_f32_e32 v194, v194
	v_exp_f32_e32 v195, v195
	s_nop 0
	v_pk_add_f32 v[192:193], v[192:193], 1.0 op_sel_hi:[1,0]
	v_pk_add_f32 v[194:195], v[194:195], 1.0 op_sel_hi:[1,0]
	v_div_scale_f32 v224, s[8:9], v192, v192, 1.0
	v_div_scale_f32 v229, s[8:9], v193, v193, 1.0
	v_div_scale_f32 v234, s[8:9], v194, v194, 1.0
	v_div_scale_f32 v239, s[8:9], v195, v195, 1.0
	v_div_scale_f32 v225, s[20:21], 1.0, v192, 1.0
	v_div_scale_f32 v230, s[22:23], 1.0, v193, 1.0
	v_div_scale_f32 v235, s[24:25], 1.0, v194, 1.0
	v_div_scale_f32 v240, s[26:27], 1.0, v195, 1.0
	v_rcp_f32_e32 v226, v224
	v_rcp_f32_e32 v231, v229
	v_rcp_f32_e32 v236, v234
	v_rcp_f32_e32 v241, v239
	v_fma_f32 v228, -v224, v226, 1.0
	v_fma_f32 v233, -v229, v231, 1.0
	v_fma_f32 v238, -v234, v236, 1.0
	v_fma_f32 v243, -v239, v241, 1.0
	v_fmac_f32_e32 v226, v228, v226
	v_fmac_f32_e32 v231, v233, v231
	v_fmac_f32_e32 v236, v238, v236
	v_fmac_f32_e32 v241, v243, v241
	v_mul_f32_e32 v227, v225, v226
	v_mul_f32_e32 v232, v230, v231
	v_mul_f32_e32 v237, v235, v236
	v_mul_f32_e32 v242, v240, v241
	v_fma_f32 v228, -v224, v227, v225
	v_fma_f32 v233, -v229, v232, v230
	v_fma_f32 v238, -v234, v237, v235
	v_fma_f32 v243, -v239, v242, v240
	v_fmac_f32_e32 v227, v228, v226
	v_fmac_f32_e32 v232, v233, v231
	v_fmac_f32_e32 v237, v238, v236
	v_fmac_f32_e32 v242, v243, v241
	v_fma_f32 v228, -v224, v227, v225
	v_fma_f32 v233, -v229, v232, v230
	v_fma_f32 v238, -v234, v237, v235
	v_fma_f32 v243, -v239, v242, v240
	s_mov_b64 vcc, s[20:21]
	s_nop 0
	v_div_fmas_f32 v228, v228, v226, v227
	s_mov_b64 vcc, s[22:23]
	s_nop 0
	v_div_fmas_f32 v233, v233, v231, v232
	s_mov_b64 vcc, s[24:25]
	s_nop 0
	v_div_fmas_f32 v238, v238, v236, v237
	s_mov_b64 vcc, s[26:27]
	s_nop 0
	v_div_fmas_f32 v243, v243, v241, v242
	v_div_fixup_f32 v196, v228, v192, 1.0
	v_div_fixup_f32 v197, v233, v193, 1.0
	v_div_fixup_f32 v198, v238, v194, 1.0
	v_div_fixup_f32 v199, v243, v195, 1.0
	v_pk_mul_f32 v[196:197], v[188:189], v[196:197]
	v_pk_mul_f32 v[198:199], v[190:191], v[198:199]
	v_pk_mul_f32 v[196:197], v[184:185], v[196:197]
	v_pk_mul_f32 v[198:199], v[186:187], v[198:199]
	v_cvt_pk_bf16_f32 v206, v196, v197
	v_cvt_pk_bf16_f32 v207, v198, v199
	global_store_dwordx2 v152, v[206:207], s[18:19]
	v_lshlrev_b32_e32 v160, 16, v14
	v_and_b32_e32 v161, 0xffff0000, v14
	v_lshlrev_b32_e32 v162, 16, v15
	v_and_b32_e32 v163, 0xffff0000, v15
	v_lshlrev_b32_e32 v172, 16, v34
	v_and_b32_e32 v173, 0xffff0000, v34
	v_lshlrev_b32_e32 v174, 16, v35
	v_and_b32_e32 v175, 0xffff0000, v35
	v_pk_mul_f32 v[184:185], v[48:49], v[168:169]
	v_pk_mul_f32 v[188:189], v[64:65], v[180:181]
	v_pk_mul_f32 v[186:187], v[50:51], v[170:171]
	v_pk_mul_f32 v[190:191], v[66:67], v[182:183]
	v_pk_fma_f32 v[184:185], v[52:53], v[164:165], v[184:185]
	v_pk_fma_f32 v[188:189], v[68:69], v[176:177], v[188:189]
	v_pk_fma_f32 v[186:187], v[54:55], v[166:167], v[186:187]
	v_pk_fma_f32 v[190:191], v[70:71], v[178:179], v[190:191]
	v_pk_fma_f32 v[184:185], v[56:57], v[160:161], v[184:185]
	v_pk_fma_f32 v[188:189], v[72:73], v[172:173], v[188:189]
	v_pk_fma_f32 v[186:187], v[58:59], v[162:163], v[186:187]
	v_pk_fma_f32 v[190:191], v[74:75], v[174:175], v[190:191]
	v_pk_add_f32 v[184:185], v[184:185], v[60:61]
	v_pk_add_f32 v[188:189], v[188:189], v[76:77]
	v_pk_add_f32 v[186:187], v[186:187], v[62:63]
	v_pk_add_f32 v[190:191], v[190:191], v[78:79]
	v_mul_f32_e32 v192, 0xbfb8aa3b, v188
	v_mul_f32_e32 v193, 0xbfb8aa3b, v189
	v_mul_f32_e32 v194, 0xbfb8aa3b, v190
	v_mul_f32_e32 v195, 0xbfb8aa3b, v191
	v_exp_f32_e32 v192, v192
	v_exp_f32_e32 v193, v193
	v_exp_f32_e32 v194, v194
	v_exp_f32_e32 v195, v195
	s_nop 0
	v_pk_add_f32 v[192:193], v[192:193], 1.0 op_sel_hi:[1,0]
	v_pk_add_f32 v[194:195], v[194:195], 1.0 op_sel_hi:[1,0]
	v_div_scale_f32 v224, s[8:9], v192, v192, 1.0
	v_div_scale_f32 v229, s[8:9], v193, v193, 1.0
	v_div_scale_f32 v234, s[8:9], v194, v194, 1.0
	v_div_scale_f32 v239, s[8:9], v195, v195, 1.0
	v_div_scale_f32 v225, s[20:21], 1.0, v192, 1.0
	v_div_scale_f32 v230, s[22:23], 1.0, v193, 1.0
	v_div_scale_f32 v235, s[24:25], 1.0, v194, 1.0
	v_div_scale_f32 v240, s[26:27], 1.0, v195, 1.0
	v_rcp_f32_e32 v226, v224
	v_rcp_f32_e32 v231, v229
	v_rcp_f32_e32 v236, v234
	v_rcp_f32_e32 v241, v239
	v_fma_f32 v228, -v224, v226, 1.0
	v_fma_f32 v233, -v229, v231, 1.0
	v_fma_f32 v238, -v234, v236, 1.0
	v_fma_f32 v243, -v239, v241, 1.0
	v_fmac_f32_e32 v226, v228, v226
	v_fmac_f32_e32 v231, v233, v231
	v_fmac_f32_e32 v236, v238, v236
	v_fmac_f32_e32 v241, v243, v241
	v_mul_f32_e32 v227, v225, v226
	v_mul_f32_e32 v232, v230, v231
	v_mul_f32_e32 v237, v235, v236
	v_mul_f32_e32 v242, v240, v241
	v_fma_f32 v228, -v224, v227, v225
	v_fma_f32 v233, -v229, v232, v230
	v_fma_f32 v238, -v234, v237, v235
	v_fma_f32 v243, -v239, v242, v240
	v_fmac_f32_e32 v227, v228, v226
	v_fmac_f32_e32 v232, v233, v231
	v_fmac_f32_e32 v237, v238, v236
	v_fmac_f32_e32 v242, v243, v241
	v_fma_f32 v228, -v224, v227, v225
	v_fma_f32 v233, -v229, v232, v230
	v_fma_f32 v238, -v234, v237, v235
	v_fma_f32 v243, -v239, v242, v240
	s_mov_b64 vcc, s[20:21]
	s_nop 0
	v_div_fmas_f32 v228, v228, v226, v227
	s_mov_b64 vcc, s[22:23]
	s_nop 0
	v_div_fmas_f32 v233, v233, v231, v232
	s_mov_b64 vcc, s[24:25]
	s_nop 0
	v_div_fmas_f32 v238, v238, v236, v237
	s_mov_b64 vcc, s[26:27]
	s_nop 0
	v_div_fmas_f32 v243, v243, v241, v242
	v_div_fixup_f32 v196, v228, v192, 1.0
	v_div_fixup_f32 v197, v233, v193, 1.0
	v_div_fixup_f32 v198, v238, v194, 1.0
	v_div_fixup_f32 v199, v243, v195, 1.0
	v_pk_mul_f32 v[196:197], v[188:189], v[196:197]
	v_pk_mul_f32 v[198:199], v[190:191], v[198:199]
	v_pk_mul_f32 v[196:197], v[184:185], v[196:197]
	v_pk_mul_f32 v[198:199], v[186:187], v[198:199]
	v_cvt_pk_bf16_f32 v208, v196, v197
	v_cvt_pk_bf16_f32 v209, v198, v199
	v_add_u32_e32 v152, 0x2c00, v152
	global_store_dwordx2 v152, v[208:209], s[18:19]
	v_lshlrev_b32_e32 v164, 16, v16
	v_and_b32_e32 v165, 0xffff0000, v16
	v_lshlrev_b32_e32 v166, 16, v17
	v_and_b32_e32 v167, 0xffff0000, v17
	v_lshlrev_b32_e32 v176, 16, v36
	v_and_b32_e32 v177, 0xffff0000, v36
	v_lshlrev_b32_e32 v178, 16, v37
	v_and_b32_e32 v179, 0xffff0000, v37
	v_pk_mul_f32 v[184:185], v[48:49], v[160:161]
	v_pk_mul_f32 v[188:189], v[64:65], v[172:173]
	v_pk_mul_f32 v[186:187], v[50:51], v[162:163]
	v_pk_mul_f32 v[190:191], v[66:67], v[174:175]
	v_pk_fma_f32 v[184:185], v[52:53], v[168:169], v[184:185]
	v_pk_fma_f32 v[188:189], v[68:69], v[180:181], v[188:189]
	v_pk_fma_f32 v[186:187], v[54:55], v[170:171], v[186:187]
	v_pk_fma_f32 v[190:191], v[70:71], v[182:183], v[190:191]
	v_pk_fma_f32 v[184:185], v[56:57], v[164:165], v[184:185]
	v_pk_fma_f32 v[188:189], v[72:73], v[176:177], v[188:189]
	v_pk_fma_f32 v[186:187], v[58:59], v[166:167], v[186:187]
	v_pk_fma_f32 v[190:191], v[74:75], v[178:179], v[190:191]
	v_pk_add_f32 v[184:185], v[184:185], v[60:61]
	v_pk_add_f32 v[188:189], v[188:189], v[76:77]
	v_pk_add_f32 v[186:187], v[186:187], v[62:63]
	v_pk_add_f32 v[190:191], v[190:191], v[78:79]
	v_mul_f32_e32 v192, 0xbfb8aa3b, v188
	v_mul_f32_e32 v193, 0xbfb8aa3b, v189
	v_mul_f32_e32 v194, 0xbfb8aa3b, v190
	v_mul_f32_e32 v195, 0xbfb8aa3b, v191
	v_exp_f32_e32 v192, v192
	v_exp_f32_e32 v193, v193
	v_exp_f32_e32 v194, v194
	v_exp_f32_e32 v195, v195
	s_nop 0
	v_pk_add_f32 v[192:193], v[192:193], 1.0 op_sel_hi:[1,0]
	v_pk_add_f32 v[194:195], v[194:195], 1.0 op_sel_hi:[1,0]
	v_div_scale_f32 v224, s[8:9], v192, v192, 1.0
	v_div_scale_f32 v229, s[8:9], v193, v193, 1.0
	v_div_scale_f32 v234, s[8:9], v194, v194, 1.0
	v_div_scale_f32 v239, s[8:9], v195, v195, 1.0
	v_div_scale_f32 v225, s[20:21], 1.0, v192, 1.0
	v_div_scale_f32 v230, s[22:23], 1.0, v193, 1.0
	v_div_scale_f32 v235, s[24:25], 1.0, v194, 1.0
	v_div_scale_f32 v240, s[26:27], 1.0, v195, 1.0
	v_rcp_f32_e32 v226, v224
	v_rcp_f32_e32 v231, v229
	v_rcp_f32_e32 v236, v234
	v_rcp_f32_e32 v241, v239
	v_fma_f32 v228, -v224, v226, 1.0
	v_fma_f32 v233, -v229, v231, 1.0
	v_fma_f32 v238, -v234, v236, 1.0
	v_fma_f32 v243, -v239, v241, 1.0
	v_fmac_f32_e32 v226, v228, v226
	v_fmac_f32_e32 v231, v233, v231
	v_fmac_f32_e32 v236, v238, v236
	v_fmac_f32_e32 v241, v243, v241
	v_mul_f32_e32 v227, v225, v226
	v_mul_f32_e32 v232, v230, v231
	v_mul_f32_e32 v237, v235, v236
	v_mul_f32_e32 v242, v240, v241
	v_fma_f32 v228, -v224, v227, v225
	v_fma_f32 v233, -v229, v232, v230
	v_fma_f32 v238, -v234, v237, v235
	v_fma_f32 v243, -v239, v242, v240
	v_fmac_f32_e32 v227, v228, v226
	v_fmac_f32_e32 v232, v233, v231
	v_fmac_f32_e32 v237, v238, v236
	v_fmac_f32_e32 v242, v243, v241
	v_fma_f32 v228, -v224, v227, v225
	v_fma_f32 v233, -v229, v232, v230
	v_fma_f32 v238, -v234, v237, v235
	v_fma_f32 v243, -v239, v242, v240
	s_mov_b64 vcc, s[20:21]
	s_nop 0
	v_div_fmas_f32 v228, v228, v226, v227
	s_mov_b64 vcc, s[22:23]
	s_nop 0
	v_div_fmas_f32 v233, v233, v231, v232
	s_mov_b64 vcc, s[24:25]
	s_nop 0
	v_div_fmas_f32 v238, v238, v236, v237
	s_mov_b64 vcc, s[26:27]
	s_nop 0
	v_div_fmas_f32 v243, v243, v241, v242
	v_div_fixup_f32 v196, v228, v192, 1.0
	v_div_fixup_f32 v197, v233, v193, 1.0
	v_div_fixup_f32 v198, v238, v194, 1.0
	v_div_fixup_f32 v199, v243, v195, 1.0
	v_pk_mul_f32 v[196:197], v[188:189], v[196:197]
	v_pk_mul_f32 v[198:199], v[190:191], v[198:199]
	v_pk_mul_f32 v[196:197], v[184:185], v[196:197]
	v_pk_mul_f32 v[198:199], v[186:187], v[198:199]
	v_cvt_pk_bf16_f32 v206, v196, v197
	v_cvt_pk_bf16_f32 v207, v198, v199
	v_add_u32_e32 v152, 0x2c00, v152
	global_store_dwordx2 v152, v[206:207], s[18:19]
	v_lshlrev_b32_e32 v168, 16, v18
	v_and_b32_e32 v169, 0xffff0000, v18
	v_lshlrev_b32_e32 v170, 16, v19
	v_and_b32_e32 v171, 0xffff0000, v19
	v_lshlrev_b32_e32 v180, 16, v38
	v_and_b32_e32 v181, 0xffff0000, v38
	v_lshlrev_b32_e32 v182, 16, v39
	v_and_b32_e32 v183, 0xffff0000, v39
	v_pk_mul_f32 v[184:185], v[48:49], v[164:165]
	v_pk_mul_f32 v[188:189], v[64:65], v[176:177]
	v_pk_mul_f32 v[186:187], v[50:51], v[166:167]
	v_pk_mul_f32 v[190:191], v[66:67], v[178:179]
	v_pk_fma_f32 v[184:185], v[52:53], v[160:161], v[184:185]
	v_pk_fma_f32 v[188:189], v[68:69], v[172:173], v[188:189]
	v_pk_fma_f32 v[186:187], v[54:55], v[162:163], v[186:187]
	v_pk_fma_f32 v[190:191], v[70:71], v[174:175], v[190:191]
	v_pk_fma_f32 v[184:185], v[56:57], v[168:169], v[184:185]
	v_pk_fma_f32 v[188:189], v[72:73], v[180:181], v[188:189]
	v_pk_fma_f32 v[186:187], v[58:59], v[170:171], v[186:187]
	v_pk_fma_f32 v[190:191], v[74:75], v[182:183], v[190:191]
	v_pk_add_f32 v[184:185], v[184:185], v[60:61]
	v_pk_add_f32 v[188:189], v[188:189], v[76:77]
	v_pk_add_f32 v[186:187], v[186:187], v[62:63]
	v_pk_add_f32 v[190:191], v[190:191], v[78:79]
	v_mul_f32_e32 v192, 0xbfb8aa3b, v188
	v_mul_f32_e32 v193, 0xbfb8aa3b, v189
	v_mul_f32_e32 v194, 0xbfb8aa3b, v190
	v_mul_f32_e32 v195, 0xbfb8aa3b, v191
	v_exp_f32_e32 v192, v192
	v_exp_f32_e32 v193, v193
	v_exp_f32_e32 v194, v194
	v_exp_f32_e32 v195, v195
	s_nop 0
	v_pk_add_f32 v[192:193], v[192:193], 1.0 op_sel_hi:[1,0]
	v_pk_add_f32 v[194:195], v[194:195], 1.0 op_sel_hi:[1,0]
	v_div_scale_f32 v224, s[8:9], v192, v192, 1.0
	v_div_scale_f32 v229, s[8:9], v193, v193, 1.0
	v_div_scale_f32 v234, s[8:9], v194, v194, 1.0
	v_div_scale_f32 v239, s[8:9], v195, v195, 1.0
	v_div_scale_f32 v225, s[20:21], 1.0, v192, 1.0
	v_div_scale_f32 v230, s[22:23], 1.0, v193, 1.0
	v_div_scale_f32 v235, s[24:25], 1.0, v194, 1.0
	v_div_scale_f32 v240, s[26:27], 1.0, v195, 1.0
	v_rcp_f32_e32 v226, v224
	v_rcp_f32_e32 v231, v229
	v_rcp_f32_e32 v236, v234
	v_rcp_f32_e32 v241, v239
	v_fma_f32 v228, -v224, v226, 1.0
	v_fma_f32 v233, -v229, v231, 1.0
	v_fma_f32 v238, -v234, v236, 1.0
	v_fma_f32 v243, -v239, v241, 1.0
	v_fmac_f32_e32 v226, v228, v226
	v_fmac_f32_e32 v231, v233, v231
	v_fmac_f32_e32 v236, v238, v236
	v_fmac_f32_e32 v241, v243, v241
	v_mul_f32_e32 v227, v225, v226
	v_mul_f32_e32 v232, v230, v231
	v_mul_f32_e32 v237, v235, v236
	v_mul_f32_e32 v242, v240, v241
	v_fma_f32 v228, -v224, v227, v225
	v_fma_f32 v233, -v229, v232, v230
	v_fma_f32 v238, -v234, v237, v235
	v_fma_f32 v243, -v239, v242, v240
	v_fmac_f32_e32 v227, v228, v226
	v_fmac_f32_e32 v232, v233, v231
	v_fmac_f32_e32 v237, v238, v236
	v_fmac_f32_e32 v242, v243, v241
	v_fma_f32 v228, -v224, v227, v225
	v_fma_f32 v233, -v229, v232, v230
	v_fma_f32 v238, -v234, v237, v235
	v_fma_f32 v243, -v239, v242, v240
	s_mov_b64 vcc, s[20:21]
	s_nop 0
	v_div_fmas_f32 v228, v228, v226, v227
	s_mov_b64 vcc, s[22:23]
	s_nop 0
	v_div_fmas_f32 v233, v233, v231, v232
	s_mov_b64 vcc, s[24:25]
	s_nop 0
	v_div_fmas_f32 v238, v238, v236, v237
	s_mov_b64 vcc, s[26:27]
	s_nop 0
	v_div_fmas_f32 v243, v243, v241, v242
	v_div_fixup_f32 v196, v228, v192, 1.0
	v_div_fixup_f32 v197, v233, v193, 1.0
	v_div_fixup_f32 v198, v238, v194, 1.0
	v_div_fixup_f32 v199, v243, v195, 1.0
	v_pk_mul_f32 v[196:197], v[188:189], v[196:197]
	v_pk_mul_f32 v[198:199], v[190:191], v[198:199]
	v_pk_mul_f32 v[196:197], v[184:185], v[196:197]
	v_pk_mul_f32 v[198:199], v[186:187], v[198:199]
	v_cvt_pk_bf16_f32 v208, v196, v197
	v_cvt_pk_bf16_f32 v209, v198, v199
	v_add_u32_e32 v152, 0x2c00, v152
	global_store_dwordx2 v152, v[208:209], s[18:19]
	v_lshlrev_b32_e32 v160, 16, v20
	v_and_b32_e32 v161, 0xffff0000, v20
	v_lshlrev_b32_e32 v162, 16, v21
	v_and_b32_e32 v163, 0xffff0000, v21
	v_lshlrev_b32_e32 v172, 16, v40
	v_and_b32_e32 v173, 0xffff0000, v40
	v_lshlrev_b32_e32 v174, 16, v41
	v_and_b32_e32 v175, 0xffff0000, v41
	v_pk_mul_f32 v[184:185], v[48:49], v[168:169]
	v_pk_mul_f32 v[188:189], v[64:65], v[180:181]
	v_pk_mul_f32 v[186:187], v[50:51], v[170:171]
	v_pk_mul_f32 v[190:191], v[66:67], v[182:183]
	v_pk_fma_f32 v[184:185], v[52:53], v[164:165], v[184:185]
	v_pk_fma_f32 v[188:189], v[68:69], v[176:177], v[188:189]
	v_pk_fma_f32 v[186:187], v[54:55], v[166:167], v[186:187]
	v_pk_fma_f32 v[190:191], v[70:71], v[178:179], v[190:191]
	v_pk_fma_f32 v[184:185], v[56:57], v[160:161], v[184:185]
	v_pk_fma_f32 v[188:189], v[72:73], v[172:173], v[188:189]
	v_pk_fma_f32 v[186:187], v[58:59], v[162:163], v[186:187]
	v_pk_fma_f32 v[190:191], v[74:75], v[174:175], v[190:191]
	v_pk_add_f32 v[184:185], v[184:185], v[60:61]
	v_pk_add_f32 v[188:189], v[188:189], v[76:77]
	v_pk_add_f32 v[186:187], v[186:187], v[62:63]
	v_pk_add_f32 v[190:191], v[190:191], v[78:79]
	v_mul_f32_e32 v192, 0xbfb8aa3b, v188
	v_mul_f32_e32 v193, 0xbfb8aa3b, v189
	v_mul_f32_e32 v194, 0xbfb8aa3b, v190
	v_mul_f32_e32 v195, 0xbfb8aa3b, v191
	v_exp_f32_e32 v192, v192
	v_exp_f32_e32 v193, v193
	v_exp_f32_e32 v194, v194
	v_exp_f32_e32 v195, v195
	s_nop 0
	v_pk_add_f32 v[192:193], v[192:193], 1.0 op_sel_hi:[1,0]
	v_pk_add_f32 v[194:195], v[194:195], 1.0 op_sel_hi:[1,0]
	v_div_scale_f32 v224, s[8:9], v192, v192, 1.0
	v_div_scale_f32 v229, s[8:9], v193, v193, 1.0
	v_div_scale_f32 v234, s[8:9], v194, v194, 1.0
	v_div_scale_f32 v239, s[8:9], v195, v195, 1.0
	v_div_scale_f32 v225, s[20:21], 1.0, v192, 1.0
	v_div_scale_f32 v230, s[22:23], 1.0, v193, 1.0
	v_div_scale_f32 v235, s[24:25], 1.0, v194, 1.0
	v_div_scale_f32 v240, s[26:27], 1.0, v195, 1.0
	v_rcp_f32_e32 v226, v224
	v_rcp_f32_e32 v231, v229
	v_rcp_f32_e32 v236, v234
	v_rcp_f32_e32 v241, v239
	v_fma_f32 v228, -v224, v226, 1.0
	v_fma_f32 v233, -v229, v231, 1.0
	v_fma_f32 v238, -v234, v236, 1.0
	v_fma_f32 v243, -v239, v241, 1.0
	v_fmac_f32_e32 v226, v228, v226
	v_fmac_f32_e32 v231, v233, v231
	v_fmac_f32_e32 v236, v238, v236
	v_fmac_f32_e32 v241, v243, v241
	v_mul_f32_e32 v227, v225, v226
	v_mul_f32_e32 v232, v230, v231
	v_mul_f32_e32 v237, v235, v236
	v_mul_f32_e32 v242, v240, v241
	v_fma_f32 v228, -v224, v227, v225
	v_fma_f32 v233, -v229, v232, v230
	v_fma_f32 v238, -v234, v237, v235
	v_fma_f32 v243, -v239, v242, v240
	v_fmac_f32_e32 v227, v228, v226
	v_fmac_f32_e32 v232, v233, v231
	v_fmac_f32_e32 v237, v238, v236
	v_fmac_f32_e32 v242, v243, v241
	v_fma_f32 v228, -v224, v227, v225
	v_fma_f32 v233, -v229, v232, v230
	v_fma_f32 v238, -v234, v237, v235
	v_fma_f32 v243, -v239, v242, v240
	s_mov_b64 vcc, s[20:21]
	s_nop 0
	v_div_fmas_f32 v228, v228, v226, v227
	s_mov_b64 vcc, s[22:23]
	s_nop 0
	v_div_fmas_f32 v233, v233, v231, v232
	s_mov_b64 vcc, s[24:25]
	s_nop 0
	v_div_fmas_f32 v238, v238, v236, v237
	s_mov_b64 vcc, s[26:27]
	s_nop 0
	v_div_fmas_f32 v243, v243, v241, v242
	v_div_fixup_f32 v196, v228, v192, 1.0
	v_div_fixup_f32 v197, v233, v193, 1.0
	v_div_fixup_f32 v198, v238, v194, 1.0
	v_div_fixup_f32 v199, v243, v195, 1.0
	v_pk_mul_f32 v[196:197], v[188:189], v[196:197]
	v_pk_mul_f32 v[198:199], v[190:191], v[198:199]
	v_pk_mul_f32 v[196:197], v[184:185], v[196:197]
	v_pk_mul_f32 v[198:199], v[186:187], v[198:199]
	v_cvt_pk_bf16_f32 v206, v196, v197
	v_cvt_pk_bf16_f32 v207, v198, v199
	v_add_u32_e32 v152, 0x2c00, v152
	global_store_dwordx2 v152, v[206:207], s[18:19]
	v_lshlrev_b32_e32 v164, 16, v22
	v_and_b32_e32 v165, 0xffff0000, v22
	v_lshlrev_b32_e32 v166, 16, v23
	v_and_b32_e32 v167, 0xffff0000, v23
	v_lshlrev_b32_e32 v176, 16, v42
	v_and_b32_e32 v177, 0xffff0000, v42
	v_lshlrev_b32_e32 v178, 16, v43
	v_and_b32_e32 v179, 0xffff0000, v43
	v_pk_mul_f32 v[184:185], v[48:49], v[160:161]
	v_pk_mul_f32 v[188:189], v[64:65], v[172:173]
	v_pk_mul_f32 v[186:187], v[50:51], v[162:163]
	v_pk_mul_f32 v[190:191], v[66:67], v[174:175]
	v_pk_fma_f32 v[184:185], v[52:53], v[168:169], v[184:185]
	v_pk_fma_f32 v[188:189], v[68:69], v[180:181], v[188:189]
	v_pk_fma_f32 v[186:187], v[54:55], v[170:171], v[186:187]
	v_pk_fma_f32 v[190:191], v[70:71], v[182:183], v[190:191]
	v_pk_fma_f32 v[184:185], v[56:57], v[164:165], v[184:185]
	v_pk_fma_f32 v[188:189], v[72:73], v[176:177], v[188:189]
	v_pk_fma_f32 v[186:187], v[58:59], v[166:167], v[186:187]
	v_pk_fma_f32 v[190:191], v[74:75], v[178:179], v[190:191]
	v_pk_add_f32 v[184:185], v[184:185], v[60:61]
	v_pk_add_f32 v[188:189], v[188:189], v[76:77]
	v_pk_add_f32 v[186:187], v[186:187], v[62:63]
	v_pk_add_f32 v[190:191], v[190:191], v[78:79]
	v_mul_f32_e32 v192, 0xbfb8aa3b, v188
	v_mul_f32_e32 v193, 0xbfb8aa3b, v189
	v_mul_f32_e32 v194, 0xbfb8aa3b, v190
	v_mul_f32_e32 v195, 0xbfb8aa3b, v191
	v_exp_f32_e32 v192, v192
	v_exp_f32_e32 v193, v193
	v_exp_f32_e32 v194, v194
	v_exp_f32_e32 v195, v195
	s_nop 0
	v_pk_add_f32 v[192:193], v[192:193], 1.0 op_sel_hi:[1,0]
	v_pk_add_f32 v[194:195], v[194:195], 1.0 op_sel_hi:[1,0]
	v_div_scale_f32 v224, s[8:9], v192, v192, 1.0
	v_div_scale_f32 v229, s[8:9], v193, v193, 1.0
	v_div_scale_f32 v234, s[8:9], v194, v194, 1.0
	v_div_scale_f32 v239, s[8:9], v195, v195, 1.0
	v_div_scale_f32 v225, s[20:21], 1.0, v192, 1.0
	v_div_scale_f32 v230, s[22:23], 1.0, v193, 1.0
	v_div_scale_f32 v235, s[24:25], 1.0, v194, 1.0
	v_div_scale_f32 v240, s[26:27], 1.0, v195, 1.0
	v_rcp_f32_e32 v226, v224
	v_rcp_f32_e32 v231, v229
	v_rcp_f32_e32 v236, v234
	v_rcp_f32_e32 v241, v239
	v_fma_f32 v228, -v224, v226, 1.0
	v_fma_f32 v233, -v229, v231, 1.0
	v_fma_f32 v238, -v234, v236, 1.0
	v_fma_f32 v243, -v239, v241, 1.0
	v_fmac_f32_e32 v226, v228, v226
	v_fmac_f32_e32 v231, v233, v231
	v_fmac_f32_e32 v236, v238, v236
	v_fmac_f32_e32 v241, v243, v241
	v_mul_f32_e32 v227, v225, v226
	v_mul_f32_e32 v232, v230, v231
	v_mul_f32_e32 v237, v235, v236
	v_mul_f32_e32 v242, v240, v241
	v_fma_f32 v228, -v224, v227, v225
	v_fma_f32 v233, -v229, v232, v230
	v_fma_f32 v238, -v234, v237, v235
	v_fma_f32 v243, -v239, v242, v240
	v_fmac_f32_e32 v227, v228, v226
	v_fmac_f32_e32 v232, v233, v231
	v_fmac_f32_e32 v237, v238, v236
	v_fmac_f32_e32 v242, v243, v241
	v_fma_f32 v228, -v224, v227, v225
	v_fma_f32 v233, -v229, v232, v230
	v_fma_f32 v238, -v234, v237, v235
	v_fma_f32 v243, -v239, v242, v240
	s_mov_b64 vcc, s[20:21]
	s_nop 0
	v_div_fmas_f32 v228, v228, v226, v227
	s_mov_b64 vcc, s[22:23]
	s_nop 0
	v_div_fmas_f32 v233, v233, v231, v232
	s_mov_b64 vcc, s[24:25]
	s_nop 0
	v_div_fmas_f32 v238, v238, v236, v237
	s_mov_b64 vcc, s[26:27]
	s_nop 0
	v_div_fmas_f32 v243, v243, v241, v242
	v_div_fixup_f32 v196, v228, v192, 1.0
	v_div_fixup_f32 v197, v233, v193, 1.0
	v_div_fixup_f32 v198, v238, v194, 1.0
	v_div_fixup_f32 v199, v243, v195, 1.0
	v_pk_mul_f32 v[196:197], v[188:189], v[196:197]
	v_pk_mul_f32 v[198:199], v[190:191], v[198:199]
	v_pk_mul_f32 v[196:197], v[184:185], v[196:197]
	v_pk_mul_f32 v[198:199], v[186:187], v[198:199]
	v_cvt_pk_bf16_f32 v208, v196, v197
	v_cvt_pk_bf16_f32 v209, v198, v199
	v_add_u32_e32 v152, 0x2c00, v152
	global_store_dwordx2 v152, v[208:209], s[18:19]
	v_lshlrev_b32_e32 v168, 16, v24
	v_and_b32_e32 v169, 0xffff0000, v24
	v_lshlrev_b32_e32 v170, 16, v25
	v_and_b32_e32 v171, 0xffff0000, v25
	v_lshlrev_b32_e32 v180, 16, v44
	v_and_b32_e32 v181, 0xffff0000, v44
	v_lshlrev_b32_e32 v182, 16, v45
	v_and_b32_e32 v183, 0xffff0000, v45
	v_pk_mul_f32 v[184:185], v[48:49], v[164:165]
	v_pk_mul_f32 v[188:189], v[64:65], v[176:177]
	v_pk_mul_f32 v[186:187], v[50:51], v[166:167]
	v_pk_mul_f32 v[190:191], v[66:67], v[178:179]
	v_pk_fma_f32 v[184:185], v[52:53], v[160:161], v[184:185]
	v_pk_fma_f32 v[188:189], v[68:69], v[172:173], v[188:189]
	v_pk_fma_f32 v[186:187], v[54:55], v[162:163], v[186:187]
	v_pk_fma_f32 v[190:191], v[70:71], v[174:175], v[190:191]
	v_pk_fma_f32 v[184:185], v[56:57], v[168:169], v[184:185]
	v_pk_fma_f32 v[188:189], v[72:73], v[180:181], v[188:189]
	v_pk_fma_f32 v[186:187], v[58:59], v[170:171], v[186:187]
	v_pk_fma_f32 v[190:191], v[74:75], v[182:183], v[190:191]
	v_pk_add_f32 v[184:185], v[184:185], v[60:61]
	v_pk_add_f32 v[188:189], v[188:189], v[76:77]
	v_pk_add_f32 v[186:187], v[186:187], v[62:63]
	v_pk_add_f32 v[190:191], v[190:191], v[78:79]
	v_mul_f32_e32 v192, 0xbfb8aa3b, v188
	v_mul_f32_e32 v193, 0xbfb8aa3b, v189
	v_mul_f32_e32 v194, 0xbfb8aa3b, v190
	v_mul_f32_e32 v195, 0xbfb8aa3b, v191
	v_exp_f32_e32 v192, v192
	v_exp_f32_e32 v193, v193
	v_exp_f32_e32 v194, v194
	v_exp_f32_e32 v195, v195
	s_nop 0
	v_pk_add_f32 v[192:193], v[192:193], 1.0 op_sel_hi:[1,0]
	v_pk_add_f32 v[194:195], v[194:195], 1.0 op_sel_hi:[1,0]
	v_div_scale_f32 v224, s[8:9], v192, v192, 1.0
	v_div_scale_f32 v229, s[8:9], v193, v193, 1.0
	v_div_scale_f32 v234, s[8:9], v194, v194, 1.0
	v_div_scale_f32 v239, s[8:9], v195, v195, 1.0
	v_div_scale_f32 v225, s[20:21], 1.0, v192, 1.0
	v_div_scale_f32 v230, s[22:23], 1.0, v193, 1.0
	v_div_scale_f32 v235, s[24:25], 1.0, v194, 1.0
	v_div_scale_f32 v240, s[26:27], 1.0, v195, 1.0
	v_rcp_f32_e32 v226, v224
	v_rcp_f32_e32 v231, v229
	v_rcp_f32_e32 v236, v234
	v_rcp_f32_e32 v241, v239
	v_fma_f32 v228, -v224, v226, 1.0
	v_fma_f32 v233, -v229, v231, 1.0
	v_fma_f32 v238, -v234, v236, 1.0
	v_fma_f32 v243, -v239, v241, 1.0
	v_fmac_f32_e32 v226, v228, v226
	v_fmac_f32_e32 v231, v233, v231
	v_fmac_f32_e32 v236, v238, v236
	v_fmac_f32_e32 v241, v243, v241
	v_mul_f32_e32 v227, v225, v226
	v_mul_f32_e32 v232, v230, v231
	v_mul_f32_e32 v237, v235, v236
	v_mul_f32_e32 v242, v240, v241
	v_fma_f32 v228, -v224, v227, v225
	v_fma_f32 v233, -v229, v232, v230
	v_fma_f32 v238, -v234, v237, v235
	v_fma_f32 v243, -v239, v242, v240
	v_fmac_f32_e32 v227, v228, v226
	v_fmac_f32_e32 v232, v233, v231
	v_fmac_f32_e32 v237, v238, v236
	v_fmac_f32_e32 v242, v243, v241
	v_fma_f32 v228, -v224, v227, v225
	v_fma_f32 v233, -v229, v232, v230
	v_fma_f32 v238, -v234, v237, v235
	v_fma_f32 v243, -v239, v242, v240
	s_mov_b64 vcc, s[20:21]
	s_nop 0
	v_div_fmas_f32 v228, v228, v226, v227
	s_mov_b64 vcc, s[22:23]
	s_nop 0
	v_div_fmas_f32 v233, v233, v231, v232
	s_mov_b64 vcc, s[24:25]
	s_nop 0
	v_div_fmas_f32 v238, v238, v236, v237
	s_mov_b64 vcc, s[26:27]
	s_nop 0
	v_div_fmas_f32 v243, v243, v241, v242
	v_div_fixup_f32 v196, v228, v192, 1.0
	v_div_fixup_f32 v197, v233, v193, 1.0
	v_div_fixup_f32 v198, v238, v194, 1.0
	v_div_fixup_f32 v199, v243, v195, 1.0
	v_pk_mul_f32 v[196:197], v[188:189], v[196:197]
	v_pk_mul_f32 v[198:199], v[190:191], v[198:199]
	v_pk_mul_f32 v[196:197], v[184:185], v[196:197]
	v_pk_mul_f32 v[198:199], v[186:187], v[198:199]
	v_cvt_pk_bf16_f32 v206, v196, v197
	v_cvt_pk_bf16_f32 v207, v198, v199
	v_add_u32_e32 v152, 0x2c00, v152
	global_store_dwordx2 v152, v[206:207], s[18:19]
	v_lshlrev_b32_e32 v160, 16, v26
	v_and_b32_e32 v161, 0xffff0000, v26
	v_lshlrev_b32_e32 v162, 16, v27
	v_and_b32_e32 v163, 0xffff0000, v27
	v_lshlrev_b32_e32 v172, 16, v46
	v_and_b32_e32 v173, 0xffff0000, v46
	v_lshlrev_b32_e32 v174, 16, v47
	v_and_b32_e32 v175, 0xffff0000, v47
	v_pk_mul_f32 v[184:185], v[48:49], v[168:169]
	v_pk_mul_f32 v[188:189], v[64:65], v[180:181]
	v_pk_mul_f32 v[186:187], v[50:51], v[170:171]
	v_pk_mul_f32 v[190:191], v[66:67], v[182:183]
	v_pk_fma_f32 v[184:185], v[52:53], v[164:165], v[184:185]
	v_pk_fma_f32 v[188:189], v[68:69], v[176:177], v[188:189]
	v_pk_fma_f32 v[186:187], v[54:55], v[166:167], v[186:187]
	v_pk_fma_f32 v[190:191], v[70:71], v[178:179], v[190:191]
	v_pk_fma_f32 v[184:185], v[56:57], v[160:161], v[184:185]
	v_pk_fma_f32 v[188:189], v[72:73], v[172:173], v[188:189]
	v_pk_fma_f32 v[186:187], v[58:59], v[162:163], v[186:187]
	v_pk_fma_f32 v[190:191], v[74:75], v[174:175], v[190:191]
	v_pk_add_f32 v[184:185], v[184:185], v[60:61]
	v_pk_add_f32 v[188:189], v[188:189], v[76:77]
	v_pk_add_f32 v[186:187], v[186:187], v[62:63]
	v_pk_add_f32 v[190:191], v[190:191], v[78:79]
	v_mul_f32_e32 v192, 0xbfb8aa3b, v188
	v_mul_f32_e32 v193, 0xbfb8aa3b, v189
	v_mul_f32_e32 v194, 0xbfb8aa3b, v190
	v_mul_f32_e32 v195, 0xbfb8aa3b, v191
	v_exp_f32_e32 v192, v192
	v_exp_f32_e32 v193, v193
	v_exp_f32_e32 v194, v194
	v_exp_f32_e32 v195, v195
	s_nop 0
	v_pk_add_f32 v[192:193], v[192:193], 1.0 op_sel_hi:[1,0]
	v_pk_add_f32 v[194:195], v[194:195], 1.0 op_sel_hi:[1,0]
	v_div_scale_f32 v224, s[8:9], v192, v192, 1.0
	v_div_scale_f32 v229, s[8:9], v193, v193, 1.0
	v_div_scale_f32 v234, s[8:9], v194, v194, 1.0
	v_div_scale_f32 v239, s[8:9], v195, v195, 1.0
	v_div_scale_f32 v225, s[20:21], 1.0, v192, 1.0
	v_div_scale_f32 v230, s[22:23], 1.0, v193, 1.0
	v_div_scale_f32 v235, s[24:25], 1.0, v194, 1.0
	v_div_scale_f32 v240, s[26:27], 1.0, v195, 1.0
	v_rcp_f32_e32 v226, v224
	v_rcp_f32_e32 v231, v229
	v_rcp_f32_e32 v236, v234
	v_rcp_f32_e32 v241, v239
	v_fma_f32 v228, -v224, v226, 1.0
	v_fma_f32 v233, -v229, v231, 1.0
	v_fma_f32 v238, -v234, v236, 1.0
	v_fma_f32 v243, -v239, v241, 1.0
	v_fmac_f32_e32 v226, v228, v226
	v_fmac_f32_e32 v231, v233, v231
	v_fmac_f32_e32 v236, v238, v236
	v_fmac_f32_e32 v241, v243, v241
	v_mul_f32_e32 v227, v225, v226
	v_mul_f32_e32 v232, v230, v231
	v_mul_f32_e32 v237, v235, v236
	v_mul_f32_e32 v242, v240, v241
	v_fma_f32 v228, -v224, v227, v225
	v_fma_f32 v233, -v229, v232, v230
	v_fma_f32 v238, -v234, v237, v235
	v_fma_f32 v243, -v239, v242, v240
	v_fmac_f32_e32 v227, v228, v226
	v_fmac_f32_e32 v232, v233, v231
	v_fmac_f32_e32 v237, v238, v236
	v_fmac_f32_e32 v242, v243, v241
	v_fma_f32 v228, -v224, v227, v225
	v_fma_f32 v233, -v229, v232, v230
	v_fma_f32 v238, -v234, v237, v235
	v_fma_f32 v243, -v239, v242, v240
	s_mov_b64 vcc, s[20:21]
	s_nop 0
	v_div_fmas_f32 v228, v228, v226, v227
	s_mov_b64 vcc, s[22:23]
	s_nop 0
	v_div_fmas_f32 v233, v233, v231, v232
	s_mov_b64 vcc, s[24:25]
	s_nop 0
	v_div_fmas_f32 v238, v238, v236, v237
	s_mov_b64 vcc, s[26:27]
	s_nop 0
	v_div_fmas_f32 v243, v243, v241, v242
	v_div_fixup_f32 v196, v228, v192, 1.0
	v_div_fixup_f32 v197, v233, v193, 1.0
	v_div_fixup_f32 v198, v238, v194, 1.0
	v_div_fixup_f32 v199, v243, v195, 1.0
	v_pk_mul_f32 v[196:197], v[188:189], v[196:197]
	v_pk_mul_f32 v[198:199], v[190:191], v[198:199]
	v_pk_mul_f32 v[196:197], v[184:185], v[196:197]
	v_pk_mul_f32 v[198:199], v[186:187], v[198:199]
	v_cvt_pk_bf16_f32 v208, v196, v197
	v_cvt_pk_bf16_f32 v209, v198, v199
	v_add_u32_e32 v152, 0x2c00, v152
	global_store_dwordx2 v152, v[208:209], s[18:19]
	s_mov_b64 exec, s[38:39]
	s_mov_b32 s38, 0x2e8ba2e9
	s_mov_b32 s39, 0x160000
	s_cbranch_execz .Lcv_done
	v_add_u32_e32 v154, s3, v158
	v_cmp_gt_u32_e32 vcc, s39, v154
	s_and_b64 s[8:9], vcc, exec
	s_nop 0
	v_cndmask_b32_e32 v218, v158, v154, vcc
	v_mul_hi_u32 v2, v218, s38
	v_lshrrev_b32_e32 v2, 8, v2
	v_mul_u32_u24_e32 v3, 0x580, v2
	v_sub_u32_e32 v3, v218, v3
	v_lshlrev_b32_e32 v4, 3, v3
	v_and_b32_e32 v5, 0x1ff, v2
	v_cmp_eq_u32_e32 vcc, 0, v5
	s_nop 1
	v_cndmask_b32_e64 v153, 0, 1, vcc
	v_lshlrev_b32_e32 v5, 3, v2
	v_mul_u32_u24_e32 v6, 0x2c00, v5
	v_add_u32_e32 v152, v6, v4
	v_mul_u32_u24_e32 v6, 0x5800, v5
	v_add_u32_e32 v6, v6, v4
	v_add_u32_e32 v7, 0xffff5000, v6
	v_cndmask_b32_e32 v7, v7, v6, vcc
	global_load_dwordx2 v[8:9], v7, s[14:15]
	global_load_dwordx2 v[28:29], v7, s[16:17]
	v_add_u32_e32 v7, 0xffffa800, v6
	v_cndmask_b32_e32 v7, v7, v6, vcc
	global_load_dwordx2 v[10:11], v7, s[14:15]
	global_load_dwordx2 v[30:31], v7, s[16:17]
	global_load_dwordx2 v[12:13], v6, s[14:15]
	global_load_dwordx2 v[32:33], v6, s[16:17]
	v_add_u32_e32 v6, 0x5800, v6
	global_load_dwordx2 v[14:15], v6, s[14:15]
	global_load_dwordx2 v[34:35], v6, s[16:17]
	v_add_u32_e32 v6, 0x5800, v6
	global_load_dwordx2 v[16:17], v6, s[14:15]
	global_load_dwordx2 v[36:37], v6, s[16:17]
	v_add_u32_e32 v6, 0x5800, v6
	global_load_dwordx2 v[18:19], v6, s[14:15]
	global_load_dwordx2 v[38:39], v6, s[16:17]
	v_add_u32_e32 v6, 0x5800, v6
	global_load_dwordx2 v[20:21], v6, s[14:15]
	global_load_dwordx2 v[40:41], v6, s[16:17]
	v_add_u32_e32 v6, 0x5800, v6
	global_load_dwordx2 v[22:23], v6, s[14:15]
	global_load_dwordx2 v[42:43], v6, s[16:17]
	v_add_u32_e32 v6, 0x5800, v6
	global_load_dwordx2 v[24:25], v6, s[14:15]
	global_load_dwordx2 v[44:45], v6, s[16:17]
	v_add_u32_e32 v6, 0x5800, v6
	global_load_dwordx2 v[26:27], v6, s[14:15]
	global_load_dwordx2 v[46:47], v6, s[16:17]
	v_lshlrev_b32_e32 v4, 4, v3
	v_add_u32_e32 v5, 0xb000, v4
	global_load_dwordx4 v[48:51], v5, s[54:55]
	global_load_dwordx4 v[52:55], v4, s[54:55]
	v_add_u32_e32 v5, 0x16000, v4
	global_load_dwordx4 v[56:59], v5, s[54:55]
	global_load_dwordx4 v[60:63], v4, s[56:57]
	v_add_u32_e32 v5, 0x10800, v4
	global_load_dwordx4 v[64:67], v5, s[54:55]
	v_add_u32_e32 v5, 0x5800, v4
	global_load_dwordx4 v[68:71], v5, s[54:55]
	v_add_u32_e32 v5, 0x1b800, v4
	global_load_dwordx4 v[72:75], v5, s[54:55]
	v_add_u32_e32 v5, 0x5800, v4
	global_load_dwordx4 v[76:79], v5, s[56:57]
	s_mov_b64 s[38:39], s[8:9]
	s_waitcnt vmcnt(36)
	v_cmp_ne_u32_e32 vcc, 0, v157
	s_nop 1
	v_cndmask_b32_e32 v80, v80, v216, vcc
	v_cndmask_b32_e32 v81, v81, v216, vcc
	v_cndmask_b32_e32 v82, v82, v216, vcc
	v_cndmask_b32_e32 v83, v83, v216, vcc
	v_cndmask_b32_e32 v100, v100, v216, vcc
	v_cndmask_b32_e32 v101, v101, v216, vcc
	v_cndmask_b32_e32 v102, v102, v216, vcc
	v_cndmask_b32_e32 v103, v103, v216, vcc
	v_lshlrev_b32_e32 v160, 16, v80
	v_and_b32_e32 v161, 0xffff0000, v80
	v_lshlrev_b32_e32 v162, 16, v81
	v_and_b32_e32 v163, 0xffff0000, v81
	v_lshlrev_b32_e32 v172, 16, v100
	v_and_b32_e32 v173, 0xffff0000, v100
	v_lshlrev_b32_e32 v174, 16, v101
	v_and_b32_e32 v175, 0xffff0000, v101
	v_lshlrev_b32_e32 v164, 16, v82
	v_and_b32_e32 v165, 0xffff0000, v82
	v_lshlrev_b32_e32 v166, 16, v83
	v_and_b32_e32 v167, 0xffff0000, v83
	v_lshlrev_b32_e32 v176, 16, v102
	v_and_b32_e32 v177, 0xffff0000, v102
	v_lshlrev_b32_e32 v178, 16, v103
	v_and_b32_e32 v179, 0xffff0000, v103
	v_lshlrev_b32_e32 v168, 16, v84
	v_and_b32_e32 v169, 0xffff0000, v84
	v_lshlrev_b32_e32 v170, 16, v85
	v_and_b32_e32 v171, 0xffff0000, v85
	v_lshlrev_b32_e32 v180, 16, v104
	v_and_b32_e32 v181, 0xffff0000, v104
	v_lshlrev_b32_e32 v182, 16, v105
	v_and_b32_e32 v183, 0xffff0000, v105
	v_pk_mul_f32 v[184:185], v[120:121], v[164:165]
	v_pk_mul_f32 v[188:189], v[136:137], v[176:177]
	v_pk_mul_f32 v[186:187], v[122:123], v[166:167]
	v_pk_mul_f32 v[190:191], v[138:139], v[178:179]
	v_pk_fma_f32 v[184:185], v[124:125], v[160:161], v[184:185]
	v_pk_fma_f32 v[188:189], v[140:141], v[172:173], v[188:189]
	v_pk_fma_f32 v[186:187], v[126:127], v[162:163], v[186:187]
	v_pk_fma_f32 v[190:191], v[142:143], v[174:175], v[190:191]
	v_pk_fma_f32 v[184:185], v[128:129], v[168:169], v[184:185]
	v_pk_fma_f32 v[188:189], v[144:145], v[180:181], v[188:189]
	v_pk_fma_f32 v[186:187], v[130:131], v[170:171], v[186:187]
	v_pk_fma_f32 v[190:191], v[146:147], v[182:183], v[190:191]
	v_pk_add_f32 v[184:185], v[184:185], v[132:133]
	v_pk_add_f32 v[188:189], v[188:189], v[148:149]
	v_pk_add_f32 v[186:187], v[186:187], v[134:135]
	v_pk_add_f32 v[190:191], v[190:191], v[150:151]
	v_mul_f32_e32 v192, 0xbfb8aa3b, v188
	v_mul_f32_e32 v193, 0xbfb8aa3b, v189
	v_mul_f32_e32 v194, 0xbfb8aa3b, v190
	v_mul_f32_e32 v195, 0xbfb8aa3b, v191
	v_exp_f32_e32 v192, v192
	v_exp_f32_e32 v193, v193
	v_exp_f32_e32 v194, v194
	v_exp_f32_e32 v195, v195
	s_nop 0
	v_pk_add_f32 v[192:193], v[192:193], 1.0 op_sel_hi:[1,0]
	v_pk_add_f32 v[194:195], v[194:195], 1.0 op_sel_hi:[1,0]
	v_div_scale_f32 v224, s[8:9], v192, v192, 1.0
	v_div_scale_f32 v229, s[8:9], v193, v193, 1.0
	v_div_scale_f32 v234, s[8:9], v194, v194, 1.0
	v_div_scale_f32 v239, s[8:9], v195, v195, 1.0
	v_div_scale_f32 v225, s[20:21], 1.0, v192, 1.0
	v_div_scale_f32 v230, s[22:23], 1.0, v193, 1.0
	v_div_scale_f32 v235, s[24:25], 1.0, v194, 1.0
	v_div_scale_f32 v240, s[26:27], 1.0, v195, 1.0
	v_rcp_f32_e32 v226, v224
	v_rcp_f32_e32 v231, v229
	v_rcp_f32_e32 v236, v234
	v_rcp_f32_e32 v241, v239
	v_fma_f32 v228, -v224, v226, 1.0
	v_fma_f32 v233, -v229, v231, 1.0
	v_fma_f32 v238, -v234, v236, 1.0
	v_fma_f32 v243, -v239, v241, 1.0
	v_fmac_f32_e32 v226, v228, v226
	v_fmac_f32_e32 v231, v233, v231
	v_fmac_f32_e32 v236, v238, v236
	v_fmac_f32_e32 v241, v243, v241
	v_mul_f32_e32 v227, v225, v226
	v_mul_f32_e32 v232, v230, v231
	v_mul_f32_e32 v237, v235, v236
	v_mul_f32_e32 v242, v240, v241
	v_fma_f32 v228, -v224, v227, v225
	v_fma_f32 v233, -v229, v232, v230
	v_fma_f32 v238, -v234, v237, v235
	v_fma_f32 v243, -v239, v242, v240
	v_fmac_f32_e32 v227, v228, v226
	v_fmac_f32_e32 v232, v233, v231
	v_fmac_f32_e32 v237, v238, v236
	v_fmac_f32_e32 v242, v243, v241
	v_fma_f32 v228, -v224, v227, v225
	v_fma_f32 v233, -v229, v232, v230
	v_fma_f32 v238, -v234, v237, v235
	v_fma_f32 v243, -v239, v242, v240
	s_mov_b64 vcc, s[20:21]
	s_nop 0
	v_div_fmas_f32 v228, v228, v226, v227
	s_mov_b64 vcc, s[22:23]
	s_nop 0
	v_div_fmas_f32 v233, v233, v231, v232
	s_mov_b64 vcc, s[24:25]
	s_nop 0
	v_div_fmas_f32 v238, v238, v236, v237
	s_mov_b64 vcc, s[26:27]
	s_nop 0
	v_div_fmas_f32 v243, v243, v241, v242
	v_div_fixup_f32 v196, v228, v192, 1.0
	v_div_fixup_f32 v197, v233, v193, 1.0
	v_div_fixup_f32 v198, v238, v194, 1.0
	v_div_fixup_f32 v199, v243, v195, 1.0
	v_pk_mul_f32 v[196:197], v[188:189], v[196:197]
	v_pk_mul_f32 v[198:199], v[190:191], v[198:199]
	v_pk_mul_f32 v[196:197], v[184:185], v[196:197]
	v_pk_mul_f32 v[198:199], v[186:187], v[198:199]
	v_cvt_pk_bf16_f32 v206, v196, v197
	v_cvt_pk_bf16_f32 v207, v198, v199
	global_store_dwordx2 v156, v[206:207], s[18:19]
	v_lshlrev_b32_e32 v160, 16, v86
	v_and_b32_e32 v161, 0xffff0000, v86
	v_lshlrev_b32_e32 v162, 16, v87
	v_and_b32_e32 v163, 0xffff0000, v87
	v_lshlrev_b32_e32 v172, 16, v106
	v_and_b32_e32 v173, 0xffff0000, v106
	v_lshlrev_b32_e32 v174, 16, v107
	v_and_b32_e32 v175, 0xffff0000, v107
	v_pk_mul_f32 v[184:185], v[120:121], v[168:169]
	v_pk_mul_f32 v[188:189], v[136:137], v[180:181]
	v_pk_mul_f32 v[186:187], v[122:123], v[170:171]
	v_pk_mul_f32 v[190:191], v[138:139], v[182:183]
	v_pk_fma_f32 v[184:185], v[124:125], v[164:165], v[184:185]
	v_pk_fma_f32 v[188:189], v[140:141], v[176:177], v[188:189]
	v_pk_fma_f32 v[186:187], v[126:127], v[166:167], v[186:187]
	v_pk_fma_f32 v[190:191], v[142:143], v[178:179], v[190:191]
	v_pk_fma_f32 v[184:185], v[128:129], v[160:161], v[184:185]
	v_pk_fma_f32 v[188:189], v[144:145], v[172:173], v[188:189]
	v_pk_fma_f32 v[186:187], v[130:131], v[162:163], v[186:187]
	v_pk_fma_f32 v[190:191], v[146:147], v[174:175], v[190:191]
	v_pk_add_f32 v[184:185], v[184:185], v[132:133]
	v_pk_add_f32 v[188:189], v[188:189], v[148:149]
	v_pk_add_f32 v[186:187], v[186:187], v[134:135]
	v_pk_add_f32 v[190:191], v[190:191], v[150:151]
	v_mul_f32_e32 v192, 0xbfb8aa3b, v188
	v_mul_f32_e32 v193, 0xbfb8aa3b, v189
	v_mul_f32_e32 v194, 0xbfb8aa3b, v190
	v_mul_f32_e32 v195, 0xbfb8aa3b, v191
	v_exp_f32_e32 v192, v192
	v_exp_f32_e32 v193, v193
	v_exp_f32_e32 v194, v194
	v_exp_f32_e32 v195, v195
	s_nop 0
	v_pk_add_f32 v[192:193], v[192:193], 1.0 op_sel_hi:[1,0]
	v_pk_add_f32 v[194:195], v[194:195], 1.0 op_sel_hi:[1,0]
	v_div_scale_f32 v224, s[8:9], v192, v192, 1.0
	v_div_scale_f32 v229, s[8:9], v193, v193, 1.0
	v_div_scale_f32 v234, s[8:9], v194, v194, 1.0
	v_div_scale_f32 v239, s[8:9], v195, v195, 1.0
	v_div_scale_f32 v225, s[20:21], 1.0, v192, 1.0
	v_div_scale_f32 v230, s[22:23], 1.0, v193, 1.0
	v_div_scale_f32 v235, s[24:25], 1.0, v194, 1.0
	v_div_scale_f32 v240, s[26:27], 1.0, v195, 1.0
	v_rcp_f32_e32 v226, v224
	v_rcp_f32_e32 v231, v229
	v_rcp_f32_e32 v236, v234
	v_rcp_f32_e32 v241, v239
	v_fma_f32 v228, -v224, v226, 1.0
	v_fma_f32 v233, -v229, v231, 1.0
	v_fma_f32 v238, -v234, v236, 1.0
	v_fma_f32 v243, -v239, v241, 1.0
	v_fmac_f32_e32 v226, v228, v226
	v_fmac_f32_e32 v231, v233, v231
	v_fmac_f32_e32 v236, v238, v236
	v_fmac_f32_e32 v241, v243, v241
	v_mul_f32_e32 v227, v225, v226
	v_mul_f32_e32 v232, v230, v231
	v_mul_f32_e32 v237, v235, v236
	v_mul_f32_e32 v242, v240, v241
	v_fma_f32 v228, -v224, v227, v225
	v_fma_f32 v233, -v229, v232, v230
	v_fma_f32 v238, -v234, v237, v235
	v_fma_f32 v243, -v239, v242, v240
	v_fmac_f32_e32 v227, v228, v226
	v_fmac_f32_e32 v232, v233, v231
	v_fmac_f32_e32 v237, v238, v236
	v_fmac_f32_e32 v242, v243, v241
	v_fma_f32 v228, -v224, v227, v225
	v_fma_f32 v233, -v229, v232, v230
	v_fma_f32 v238, -v234, v237, v235
	v_fma_f32 v243, -v239, v242, v240
	s_mov_b64 vcc, s[20:21]
	s_nop 0
	v_div_fmas_f32 v228, v228, v226, v227
	s_mov_b64 vcc, s[22:23]
	s_nop 0
	v_div_fmas_f32 v233, v233, v231, v232
	s_mov_b64 vcc, s[24:25]
	s_nop 0
	v_div_fmas_f32 v238, v238, v236, v237
	s_mov_b64 vcc, s[26:27]
	s_nop 0
	v_div_fmas_f32 v243, v243, v241, v242
	v_div_fixup_f32 v196, v228, v192, 1.0
	v_div_fixup_f32 v197, v233, v193, 1.0
	v_div_fixup_f32 v198, v238, v194, 1.0
	v_div_fixup_f32 v199, v243, v195, 1.0
	v_pk_mul_f32 v[196:197], v[188:189], v[196:197]
	v_pk_mul_f32 v[198:199], v[190:191], v[198:199]
	v_pk_mul_f32 v[196:197], v[184:185], v[196:197]
	v_pk_mul_f32 v[198:199], v[186:187], v[198:199]
	v_cvt_pk_bf16_f32 v208, v196, v197
	v_cvt_pk_bf16_f32 v209, v198, v199
	v_add_u32_e32 v156, 0x2c00, v156
	global_store_dwordx2 v156, v[208:209], s[18:19]
	v_lshlrev_b32_e32 v164, 16, v88
	v_and_b32_e32 v165, 0xffff0000, v88
	v_lshlrev_b32_e32 v166, 16, v89
	v_and_b32_e32 v167, 0xffff0000, v89
	v_lshlrev_b32_e32 v176, 16, v108
	v_and_b32_e32 v177, 0xffff0000, v108
	v_lshlrev_b32_e32 v178, 16, v109
	v_and_b32_e32 v179, 0xffff0000, v109
	v_pk_mul_f32 v[184:185], v[120:121], v[160:161]
	v_pk_mul_f32 v[188:189], v[136:137], v[172:173]
	v_pk_mul_f32 v[186:187], v[122:123], v[162:163]
	v_pk_mul_f32 v[190:191], v[138:139], v[174:175]
	v_pk_fma_f32 v[184:185], v[124:125], v[168:169], v[184:185]
	v_pk_fma_f32 v[188:189], v[140:141], v[180:181], v[188:189]
	v_pk_fma_f32 v[186:187], v[126:127], v[170:171], v[186:187]
	v_pk_fma_f32 v[190:191], v[142:143], v[182:183], v[190:191]
	v_pk_fma_f32 v[184:185], v[128:129], v[164:165], v[184:185]
	v_pk_fma_f32 v[188:189], v[144:145], v[176:177], v[188:189]
	v_pk_fma_f32 v[186:187], v[130:131], v[166:167], v[186:187]
	v_pk_fma_f32 v[190:191], v[146:147], v[178:179], v[190:191]
	v_pk_add_f32 v[184:185], v[184:185], v[132:133]
	v_pk_add_f32 v[188:189], v[188:189], v[148:149]
	v_pk_add_f32 v[186:187], v[186:187], v[134:135]
	v_pk_add_f32 v[190:191], v[190:191], v[150:151]
	v_mul_f32_e32 v192, 0xbfb8aa3b, v188
	v_mul_f32_e32 v193, 0xbfb8aa3b, v189
	v_mul_f32_e32 v194, 0xbfb8aa3b, v190
	v_mul_f32_e32 v195, 0xbfb8aa3b, v191
	v_exp_f32_e32 v192, v192
	v_exp_f32_e32 v193, v193
	v_exp_f32_e32 v194, v194
	v_exp_f32_e32 v195, v195
	s_nop 0
	v_pk_add_f32 v[192:193], v[192:193], 1.0 op_sel_hi:[1,0]
	v_pk_add_f32 v[194:195], v[194:195], 1.0 op_sel_hi:[1,0]
	v_div_scale_f32 v224, s[8:9], v192, v192, 1.0
	v_div_scale_f32 v229, s[8:9], v193, v193, 1.0
	v_div_scale_f32 v234, s[8:9], v194, v194, 1.0
	v_div_scale_f32 v239, s[8:9], v195, v195, 1.0
	v_div_scale_f32 v225, s[20:21], 1.0, v192, 1.0
	v_div_scale_f32 v230, s[22:23], 1.0, v193, 1.0
	v_div_scale_f32 v235, s[24:25], 1.0, v194, 1.0
	v_div_scale_f32 v240, s[26:27], 1.0, v195, 1.0
	v_rcp_f32_e32 v226, v224
	v_rcp_f32_e32 v231, v229
	v_rcp_f32_e32 v236, v234
	v_rcp_f32_e32 v241, v239
	v_fma_f32 v228, -v224, v226, 1.0
	v_fma_f32 v233, -v229, v231, 1.0
	v_fma_f32 v238, -v234, v236, 1.0
	v_fma_f32 v243, -v239, v241, 1.0
	v_fmac_f32_e32 v226, v228, v226
	v_fmac_f32_e32 v231, v233, v231
	v_fmac_f32_e32 v236, v238, v236
	v_fmac_f32_e32 v241, v243, v241
	v_mul_f32_e32 v227, v225, v226
	v_mul_f32_e32 v232, v230, v231
	v_mul_f32_e32 v237, v235, v236
	v_mul_f32_e32 v242, v240, v241
	v_fma_f32 v228, -v224, v227, v225
	v_fma_f32 v233, -v229, v232, v230
	v_fma_f32 v238, -v234, v237, v235
	v_fma_f32 v243, -v239, v242, v240
	v_fmac_f32_e32 v227, v228, v226
	v_fmac_f32_e32 v232, v233, v231
	v_fmac_f32_e32 v237, v238, v236
	v_fmac_f32_e32 v242, v243, v241
	v_fma_f32 v228, -v224, v227, v225
	v_fma_f32 v233, -v229, v232, v230
	v_fma_f32 v238, -v234, v237, v235
	v_fma_f32 v243, -v239, v242, v240
	s_mov_b64 vcc, s[20:21]
	s_nop 0
	v_div_fmas_f32 v228, v228, v226, v227
	s_mov_b64 vcc, s[22:23]
	s_nop 0
	v_div_fmas_f32 v233, v233, v231, v232
	s_mov_b64 vcc, s[24:25]
	s_nop 0
	v_div_fmas_f32 v238, v238, v236, v237
	s_mov_b64 vcc, s[26:27]
	s_nop 0
	v_div_fmas_f32 v243, v243, v241, v242
	v_div_fixup_f32 v196, v228, v192, 1.0
	v_div_fixup_f32 v197, v233, v193, 1.0
	v_div_fixup_f32 v198, v238, v194, 1.0
	v_div_fixup_f32 v199, v243, v195, 1.0
	v_pk_mul_f32 v[196:197], v[188:189], v[196:197]
	v_pk_mul_f32 v[198:199], v[190:191], v[198:199]
	v_pk_mul_f32 v[196:197], v[184:185], v[196:197]
	v_pk_mul_f32 v[198:199], v[186:187], v[198:199]
	v_cvt_pk_bf16_f32 v206, v196, v197
	v_cvt_pk_bf16_f32 v207, v198, v199
	v_add_u32_e32 v156, 0x2c00, v156
	global_store_dwordx2 v156, v[206:207], s[18:19]
	v_lshlrev_b32_e32 v168, 16, v90
	v_and_b32_e32 v169, 0xffff0000, v90
	v_lshlrev_b32_e32 v170, 16, v91
	v_and_b32_e32 v171, 0xffff0000, v91
	v_lshlrev_b32_e32 v180, 16, v110
	v_and_b32_e32 v181, 0xffff0000, v110
	v_lshlrev_b32_e32 v182, 16, v111
	v_and_b32_e32 v183, 0xffff0000, v111
	v_pk_mul_f32 v[184:185], v[120:121], v[164:165]
	v_pk_mul_f32 v[188:189], v[136:137], v[176:177]
	v_pk_mul_f32 v[186:187], v[122:123], v[166:167]
	v_pk_mul_f32 v[190:191], v[138:139], v[178:179]
	v_pk_fma_f32 v[184:185], v[124:125], v[160:161], v[184:185]
	v_pk_fma_f32 v[188:189], v[140:141], v[172:173], v[188:189]
	v_pk_fma_f32 v[186:187], v[126:127], v[162:163], v[186:187]
	v_pk_fma_f32 v[190:191], v[142:143], v[174:175], v[190:191]
	v_pk_fma_f32 v[184:185], v[128:129], v[168:169], v[184:185]
	v_pk_fma_f32 v[188:189], v[144:145], v[180:181], v[188:189]
	v_pk_fma_f32 v[186:187], v[130:131], v[170:171], v[186:187]
	v_pk_fma_f32 v[190:191], v[146:147], v[182:183], v[190:191]
	v_pk_add_f32 v[184:185], v[184:185], v[132:133]
	v_pk_add_f32 v[188:189], v[188:189], v[148:149]
	v_pk_add_f32 v[186:187], v[186:187], v[134:135]
	v_pk_add_f32 v[190:191], v[190:191], v[150:151]
	v_mul_f32_e32 v192, 0xbfb8aa3b, v188
	v_mul_f32_e32 v193, 0xbfb8aa3b, v189
	v_mul_f32_e32 v194, 0xbfb8aa3b, v190
	v_mul_f32_e32 v195, 0xbfb8aa3b, v191
	v_exp_f32_e32 v192, v192
	v_exp_f32_e32 v193, v193
	v_exp_f32_e32 v194, v194
	v_exp_f32_e32 v195, v195
	s_nop 0
	v_pk_add_f32 v[192:193], v[192:193], 1.0 op_sel_hi:[1,0]
	v_pk_add_f32 v[194:195], v[194:195], 1.0 op_sel_hi:[1,0]
	v_div_scale_f32 v224, s[8:9], v192, v192, 1.0
	v_div_scale_f32 v229, s[8:9], v193, v193, 1.0
	v_div_scale_f32 v234, s[8:9], v194, v194, 1.0
	v_div_scale_f32 v239, s[8:9], v195, v195, 1.0
	v_div_scale_f32 v225, s[20:21], 1.0, v192, 1.0
	v_div_scale_f32 v230, s[22:23], 1.0, v193, 1.0
	v_div_scale_f32 v235, s[24:25], 1.0, v194, 1.0
	v_div_scale_f32 v240, s[26:27], 1.0, v195, 1.0
	v_rcp_f32_e32 v226, v224
	v_rcp_f32_e32 v231, v229
	v_rcp_f32_e32 v236, v234
	v_rcp_f32_e32 v241, v239
	v_fma_f32 v228, -v224, v226, 1.0
	v_fma_f32 v233, -v229, v231, 1.0
	v_fma_f32 v238, -v234, v236, 1.0
	v_fma_f32 v243, -v239, v241, 1.0
	v_fmac_f32_e32 v226, v228, v226
	v_fmac_f32_e32 v231, v233, v231
	v_fmac_f32_e32 v236, v238, v236
	v_fmac_f32_e32 v241, v243, v241
	v_mul_f32_e32 v227, v225, v226
	v_mul_f32_e32 v232, v230, v231
	v_mul_f32_e32 v237, v235, v236
	v_mul_f32_e32 v242, v240, v241
	v_fma_f32 v228, -v224, v227, v225
	v_fma_f32 v233, -v229, v232, v230
	v_fma_f32 v238, -v234, v237, v235
	v_fma_f32 v243, -v239, v242, v240
	v_fmac_f32_e32 v227, v228, v226
	v_fmac_f32_e32 v232, v233, v231
	v_fmac_f32_e32 v237, v238, v236
	v_fmac_f32_e32 v242, v243, v241
	v_fma_f32 v228, -v224, v227, v225
	v_fma_f32 v233, -v229, v232, v230
	v_fma_f32 v238, -v234, v237, v235
	v_fma_f32 v243, -v239, v242, v240
	s_mov_b64 vcc, s[20:21]
	s_nop 0
	v_div_fmas_f32 v228, v228, v226, v227
	s_mov_b64 vcc, s[22:23]
	s_nop 0
	v_div_fmas_f32 v233, v233, v231, v232
	s_mov_b64 vcc, s[24:25]
	s_nop 0
	v_div_fmas_f32 v238, v238, v236, v237
	s_mov_b64 vcc, s[26:27]
	s_nop 0
	v_div_fmas_f32 v243, v243, v241, v242
	v_div_fixup_f32 v196, v228, v192, 1.0
	v_div_fixup_f32 v197, v233, v193, 1.0
	v_div_fixup_f32 v198, v238, v194, 1.0
	v_div_fixup_f32 v199, v243, v195, 1.0
	v_pk_mul_f32 v[196:197], v[188:189], v[196:197]
	v_pk_mul_f32 v[198:199], v[190:191], v[198:199]
	v_pk_mul_f32 v[196:197], v[184:185], v[196:197]
	v_pk_mul_f32 v[198:199], v[186:187], v[198:199]
	v_cvt_pk_bf16_f32 v208, v196, v197
	v_cvt_pk_bf16_f32 v209, v198, v199
	v_add_u32_e32 v156, 0x2c00, v156
	global_store_dwordx2 v156, v[208:209], s[18:19]
	v_lshlrev_b32_e32 v160, 16, v92
	v_and_b32_e32 v161, 0xffff0000, v92
	v_lshlrev_b32_e32 v162, 16, v93
	v_and_b32_e32 v163, 0xffff0000, v93
	v_lshlrev_b32_e32 v172, 16, v112
	v_and_b32_e32 v173, 0xffff0000, v112
	v_lshlrev_b32_e32 v174, 16, v113
	v_and_b32_e32 v175, 0xffff0000, v113
	v_pk_mul_f32 v[184:185], v[120:121], v[168:169]
	v_pk_mul_f32 v[188:189], v[136:137], v[180:181]
	v_pk_mul_f32 v[186:187], v[122:123], v[170:171]
	v_pk_mul_f32 v[190:191], v[138:139], v[182:183]
	v_pk_fma_f32 v[184:185], v[124:125], v[164:165], v[184:185]
	v_pk_fma_f32 v[188:189], v[140:141], v[176:177], v[188:189]
	v_pk_fma_f32 v[186:187], v[126:127], v[166:167], v[186:187]
	v_pk_fma_f32 v[190:191], v[142:143], v[178:179], v[190:191]
	v_pk_fma_f32 v[184:185], v[128:129], v[160:161], v[184:185]
	v_pk_fma_f32 v[188:189], v[144:145], v[172:173], v[188:189]
	v_pk_fma_f32 v[186:187], v[130:131], v[162:163], v[186:187]
	v_pk_fma_f32 v[190:191], v[146:147], v[174:175], v[190:191]
	v_pk_add_f32 v[184:185], v[184:185], v[132:133]
	v_pk_add_f32 v[188:189], v[188:189], v[148:149]
	v_pk_add_f32 v[186:187], v[186:187], v[134:135]
	v_pk_add_f32 v[190:191], v[190:191], v[150:151]
	v_mul_f32_e32 v192, 0xbfb8aa3b, v188
	v_mul_f32_e32 v193, 0xbfb8aa3b, v189
	v_mul_f32_e32 v194, 0xbfb8aa3b, v190
	v_mul_f32_e32 v195, 0xbfb8aa3b, v191
	v_exp_f32_e32 v192, v192
	v_exp_f32_e32 v193, v193
	v_exp_f32_e32 v194, v194
	v_exp_f32_e32 v195, v195
	s_nop 0
	v_pk_add_f32 v[192:193], v[192:193], 1.0 op_sel_hi:[1,0]
	v_pk_add_f32 v[194:195], v[194:195], 1.0 op_sel_hi:[1,0]
	v_div_scale_f32 v224, s[8:9], v192, v192, 1.0
	v_div_scale_f32 v229, s[8:9], v193, v193, 1.0
	v_div_scale_f32 v234, s[8:9], v194, v194, 1.0
	v_div_scale_f32 v239, s[8:9], v195, v195, 1.0
	v_div_scale_f32 v225, s[20:21], 1.0, v192, 1.0
	v_div_scale_f32 v230, s[22:23], 1.0, v193, 1.0
	v_div_scale_f32 v235, s[24:25], 1.0, v194, 1.0
	v_div_scale_f32 v240, s[26:27], 1.0, v195, 1.0
	v_rcp_f32_e32 v226, v224
	v_rcp_f32_e32 v231, v229
	v_rcp_f32_e32 v236, v234
	v_rcp_f32_e32 v241, v239
	v_fma_f32 v228, -v224, v226, 1.0
	v_fma_f32 v233, -v229, v231, 1.0
	v_fma_f32 v238, -v234, v236, 1.0
	v_fma_f32 v243, -v239, v241, 1.0
	v_fmac_f32_e32 v226, v228, v226
	v_fmac_f32_e32 v231, v233, v231
	v_fmac_f32_e32 v236, v238, v236
	v_fmac_f32_e32 v241, v243, v241
	v_mul_f32_e32 v227, v225, v226
	v_mul_f32_e32 v232, v230, v231
	v_mul_f32_e32 v237, v235, v236
	v_mul_f32_e32 v242, v240, v241
	v_fma_f32 v228, -v224, v227, v225
	v_fma_f32 v233, -v229, v232, v230
	v_fma_f32 v238, -v234, v237, v235
	v_fma_f32 v243, -v239, v242, v240
	v_fmac_f32_e32 v227, v228, v226
	v_fmac_f32_e32 v232, v233, v231
	v_fmac_f32_e32 v237, v238, v236
	v_fmac_f32_e32 v242, v243, v241
	v_fma_f32 v228, -v224, v227, v225
	v_fma_f32 v233, -v229, v232, v230
	v_fma_f32 v238, -v234, v237, v235
	v_fma_f32 v243, -v239, v242, v240
	s_mov_b64 vcc, s[20:21]
	s_nop 0
	v_div_fmas_f32 v228, v228, v226, v227
	s_mov_b64 vcc, s[22:23]
	s_nop 0
	v_div_fmas_f32 v233, v233, v231, v232
	s_mov_b64 vcc, s[24:25]
	s_nop 0
	v_div_fmas_f32 v238, v238, v236, v237
	s_mov_b64 vcc, s[26:27]
	s_nop 0
	v_div_fmas_f32 v243, v243, v241, v242
	v_div_fixup_f32 v196, v228, v192, 1.0
	v_div_fixup_f32 v197, v233, v193, 1.0
	v_div_fixup_f32 v198, v238, v194, 1.0
	v_div_fixup_f32 v199, v243, v195, 1.0
	v_pk_mul_f32 v[196:197], v[188:189], v[196:197]
	v_pk_mul_f32 v[198:199], v[190:191], v[198:199]
	v_pk_mul_f32 v[196:197], v[184:185], v[196:197]
	v_pk_mul_f32 v[198:199], v[186:187], v[198:199]
	v_cvt_pk_bf16_f32 v206, v196, v197
	v_cvt_pk_bf16_f32 v207, v198, v199
	v_add_u32_e32 v156, 0x2c00, v156
	global_store_dwordx2 v156, v[206:207], s[18:19]
	v_lshlrev_b32_e32 v164, 16, v94
	v_and_b32_e32 v165, 0xffff0000, v94
	v_lshlrev_b32_e32 v166, 16, v95
	v_and_b32_e32 v167, 0xffff0000, v95
	v_lshlrev_b32_e32 v176, 16, v114
	v_and_b32_e32 v177, 0xffff0000, v114
	v_lshlrev_b32_e32 v178, 16, v115
	v_and_b32_e32 v179, 0xffff0000, v115
	v_pk_mul_f32 v[184:185], v[120:121], v[160:161]
	v_pk_mul_f32 v[188:189], v[136:137], v[172:173]
	v_pk_mul_f32 v[186:187], v[122:123], v[162:163]
	v_pk_mul_f32 v[190:191], v[138:139], v[174:175]
	v_pk_fma_f32 v[184:185], v[124:125], v[168:169], v[184:185]
	v_pk_fma_f32 v[188:189], v[140:141], v[180:181], v[188:189]
	v_pk_fma_f32 v[186:187], v[126:127], v[170:171], v[186:187]
	v_pk_fma_f32 v[190:191], v[142:143], v[182:183], v[190:191]
	v_pk_fma_f32 v[184:185], v[128:129], v[164:165], v[184:185]
	v_pk_fma_f32 v[188:189], v[144:145], v[176:177], v[188:189]
	v_pk_fma_f32 v[186:187], v[130:131], v[166:167], v[186:187]
	v_pk_fma_f32 v[190:191], v[146:147], v[178:179], v[190:191]
	v_pk_add_f32 v[184:185], v[184:185], v[132:133]
	v_pk_add_f32 v[188:189], v[188:189], v[148:149]
	v_pk_add_f32 v[186:187], v[186:187], v[134:135]
	v_pk_add_f32 v[190:191], v[190:191], v[150:151]
	v_mul_f32_e32 v192, 0xbfb8aa3b, v188
	v_mul_f32_e32 v193, 0xbfb8aa3b, v189
	v_mul_f32_e32 v194, 0xbfb8aa3b, v190
	v_mul_f32_e32 v195, 0xbfb8aa3b, v191
	v_exp_f32_e32 v192, v192
	v_exp_f32_e32 v193, v193
	v_exp_f32_e32 v194, v194
	v_exp_f32_e32 v195, v195
	s_nop 0
	v_pk_add_f32 v[192:193], v[192:193], 1.0 op_sel_hi:[1,0]
	v_pk_add_f32 v[194:195], v[194:195], 1.0 op_sel_hi:[1,0]
	v_div_scale_f32 v224, s[8:9], v192, v192, 1.0
	v_div_scale_f32 v229, s[8:9], v193, v193, 1.0
	v_div_scale_f32 v234, s[8:9], v194, v194, 1.0
	v_div_scale_f32 v239, s[8:9], v195, v195, 1.0
	v_div_scale_f32 v225, s[20:21], 1.0, v192, 1.0
	v_div_scale_f32 v230, s[22:23], 1.0, v193, 1.0
	v_div_scale_f32 v235, s[24:25], 1.0, v194, 1.0
	v_div_scale_f32 v240, s[26:27], 1.0, v195, 1.0
	v_rcp_f32_e32 v226, v224
	v_rcp_f32_e32 v231, v229
	v_rcp_f32_e32 v236, v234
	v_rcp_f32_e32 v241, v239
	v_fma_f32 v228, -v224, v226, 1.0
	v_fma_f32 v233, -v229, v231, 1.0
	v_fma_f32 v238, -v234, v236, 1.0
	v_fma_f32 v243, -v239, v241, 1.0
	v_fmac_f32_e32 v226, v228, v226
	v_fmac_f32_e32 v231, v233, v231
	v_fmac_f32_e32 v236, v238, v236
	v_fmac_f32_e32 v241, v243, v241
	v_mul_f32_e32 v227, v225, v226
	v_mul_f32_e32 v232, v230, v231
	v_mul_f32_e32 v237, v235, v236
	v_mul_f32_e32 v242, v240, v241
	v_fma_f32 v228, -v224, v227, v225
	v_fma_f32 v233, -v229, v232, v230
	v_fma_f32 v238, -v234, v237, v235
	v_fma_f32 v243, -v239, v242, v240
	v_fmac_f32_e32 v227, v228, v226
	v_fmac_f32_e32 v232, v233, v231
	v_fmac_f32_e32 v237, v238, v236
	v_fmac_f32_e32 v242, v243, v241
	v_fma_f32 v228, -v224, v227, v225
	v_fma_f32 v233, -v229, v232, v230
	v_fma_f32 v238, -v234, v237, v235
	v_fma_f32 v243, -v239, v242, v240
	s_mov_b64 vcc, s[20:21]
	s_nop 0
	v_div_fmas_f32 v228, v228, v226, v227
	s_mov_b64 vcc, s[22:23]
	s_nop 0
	v_div_fmas_f32 v233, v233, v231, v232
	s_mov_b64 vcc, s[24:25]
	s_nop 0
	v_div_fmas_f32 v238, v238, v236, v237
	s_mov_b64 vcc, s[26:27]
	s_nop 0
	v_div_fmas_f32 v243, v243, v241, v242
	v_div_fixup_f32 v196, v228, v192, 1.0
	v_div_fixup_f32 v197, v233, v193, 1.0
	v_div_fixup_f32 v198, v238, v194, 1.0
	v_div_fixup_f32 v199, v243, v195, 1.0
	v_pk_mul_f32 v[196:197], v[188:189], v[196:197]
	v_pk_mul_f32 v[198:199], v[190:191], v[198:199]
	v_pk_mul_f32 v[196:197], v[184:185], v[196:197]
	v_pk_mul_f32 v[198:199], v[186:187], v[198:199]
	v_cvt_pk_bf16_f32 v208, v196, v197
	v_cvt_pk_bf16_f32 v209, v198, v199
	v_add_u32_e32 v156, 0x2c00, v156
	global_store_dwordx2 v156, v[208:209], s[18:19]
	v_lshlrev_b32_e32 v168, 16, v96
	v_and_b32_e32 v169, 0xffff0000, v96
	v_lshlrev_b32_e32 v170, 16, v97
	v_and_b32_e32 v171, 0xffff0000, v97
	v_lshlrev_b32_e32 v180, 16, v116
	v_and_b32_e32 v181, 0xffff0000, v116
	v_lshlrev_b32_e32 v182, 16, v117
	v_and_b32_e32 v183, 0xffff0000, v117
	v_pk_mul_f32 v[184:185], v[120:121], v[164:165]
	v_pk_mul_f32 v[188:189], v[136:137], v[176:177]
	v_pk_mul_f32 v[186:187], v[122:123], v[166:167]
	v_pk_mul_f32 v[190:191], v[138:139], v[178:179]
	v_pk_fma_f32 v[184:185], v[124:125], v[160:161], v[184:185]
	v_pk_fma_f32 v[188:189], v[140:141], v[172:173], v[188:189]
	v_pk_fma_f32 v[186:187], v[126:127], v[162:163], v[186:187]
	v_pk_fma_f32 v[190:191], v[142:143], v[174:175], v[190:191]
	v_pk_fma_f32 v[184:185], v[128:129], v[168:169], v[184:185]
	v_pk_fma_f32 v[188:189], v[144:145], v[180:181], v[188:189]
	v_pk_fma_f32 v[186:187], v[130:131], v[170:171], v[186:187]
	v_pk_fma_f32 v[190:191], v[146:147], v[182:183], v[190:191]
	v_pk_add_f32 v[184:185], v[184:185], v[132:133]
	v_pk_add_f32 v[188:189], v[188:189], v[148:149]
	v_pk_add_f32 v[186:187], v[186:187], v[134:135]
	v_pk_add_f32 v[190:191], v[190:191], v[150:151]
	v_mul_f32_e32 v192, 0xbfb8aa3b, v188
	v_mul_f32_e32 v193, 0xbfb8aa3b, v189
	v_mul_f32_e32 v194, 0xbfb8aa3b, v190
	v_mul_f32_e32 v195, 0xbfb8aa3b, v191
	v_exp_f32_e32 v192, v192
	v_exp_f32_e32 v193, v193
	v_exp_f32_e32 v194, v194
	v_exp_f32_e32 v195, v195
	s_nop 0
	v_pk_add_f32 v[192:193], v[192:193], 1.0 op_sel_hi:[1,0]
	v_pk_add_f32 v[194:195], v[194:195], 1.0 op_sel_hi:[1,0]
	v_div_scale_f32 v224, s[8:9], v192, v192, 1.0
	v_div_scale_f32 v229, s[8:9], v193, v193, 1.0
	v_div_scale_f32 v234, s[8:9], v194, v194, 1.0
	v_div_scale_f32 v239, s[8:9], v195, v195, 1.0
	v_div_scale_f32 v225, s[20:21], 1.0, v192, 1.0
	v_div_scale_f32 v230, s[22:23], 1.0, v193, 1.0
	v_div_scale_f32 v235, s[24:25], 1.0, v194, 1.0
	v_div_scale_f32 v240, s[26:27], 1.0, v195, 1.0
	v_rcp_f32_e32 v226, v224
	v_rcp_f32_e32 v231, v229
	v_rcp_f32_e32 v236, v234
	v_rcp_f32_e32 v241, v239
	v_fma_f32 v228, -v224, v226, 1.0
	v_fma_f32 v233, -v229, v231, 1.0
	v_fma_f32 v238, -v234, v236, 1.0
	v_fma_f32 v243, -v239, v241, 1.0
	v_fmac_f32_e32 v226, v228, v226
	v_fmac_f32_e32 v231, v233, v231
	v_fmac_f32_e32 v236, v238, v236
	v_fmac_f32_e32 v241, v243, v241
	v_mul_f32_e32 v227, v225, v226
	v_mul_f32_e32 v232, v230, v231
	v_mul_f32_e32 v237, v235, v236
	v_mul_f32_e32 v242, v240, v241
	v_fma_f32 v228, -v224, v227, v225
	v_fma_f32 v233, -v229, v232, v230
	v_fma_f32 v238, -v234, v237, v235
	v_fma_f32 v243, -v239, v242, v240
	v_fmac_f32_e32 v227, v228, v226
	v_fmac_f32_e32 v232, v233, v231
	v_fmac_f32_e32 v237, v238, v236
	v_fmac_f32_e32 v242, v243, v241
	v_fma_f32 v228, -v224, v227, v225
	v_fma_f32 v233, -v229, v232, v230
	v_fma_f32 v238, -v234, v237, v235
	v_fma_f32 v243, -v239, v242, v240
	s_mov_b64 vcc, s[20:21]
	s_nop 0
	v_div_fmas_f32 v228, v228, v226, v227
	s_mov_b64 vcc, s[22:23]
	s_nop 0
	v_div_fmas_f32 v233, v233, v231, v232
	s_mov_b64 vcc, s[24:25]
	s_nop 0
	v_div_fmas_f32 v238, v238, v236, v237
	s_mov_b64 vcc, s[26:27]
	s_nop 0
	v_div_fmas_f32 v243, v243, v241, v242
	v_div_fixup_f32 v196, v228, v192, 1.0
	v_div_fixup_f32 v197, v233, v193, 1.0
	v_div_fixup_f32 v198, v238, v194, 1.0
	v_div_fixup_f32 v199, v243, v195, 1.0
	v_pk_mul_f32 v[196:197], v[188:189], v[196:197]
	v_pk_mul_f32 v[198:199], v[190:191], v[198:199]
	v_pk_mul_f32 v[196:197], v[184:185], v[196:197]
	v_pk_mul_f32 v[198:199], v[186:187], v[198:199]
	v_cvt_pk_bf16_f32 v206, v196, v197
	v_cvt_pk_bf16_f32 v207, v198, v199
	v_add_u32_e32 v156, 0x2c00, v156
	global_store_dwordx2 v156, v[206:207], s[18:19]
	v_lshlrev_b32_e32 v160, 16, v98
	v_and_b32_e32 v161, 0xffff0000, v98
	v_lshlrev_b32_e32 v162, 16, v99
	v_and_b32_e32 v163, 0xffff0000, v99
	v_lshlrev_b32_e32 v172, 16, v118
	v_and_b32_e32 v173, 0xffff0000, v118
	v_lshlrev_b32_e32 v174, 16, v119
	v_and_b32_e32 v175, 0xffff0000, v119
	v_pk_mul_f32 v[184:185], v[120:121], v[168:169]
	v_pk_mul_f32 v[188:189], v[136:137], v[180:181]
	v_pk_mul_f32 v[186:187], v[122:123], v[170:171]
	v_pk_mul_f32 v[190:191], v[138:139], v[182:183]
	v_pk_fma_f32 v[184:185], v[124:125], v[164:165], v[184:185]
	v_pk_fma_f32 v[188:189], v[140:141], v[176:177], v[188:189]
	v_pk_fma_f32 v[186:187], v[126:127], v[166:167], v[186:187]
	v_pk_fma_f32 v[190:191], v[142:143], v[178:179], v[190:191]
	v_pk_fma_f32 v[184:185], v[128:129], v[160:161], v[184:185]
	v_pk_fma_f32 v[188:189], v[144:145], v[172:173], v[188:189]
	v_pk_fma_f32 v[186:187], v[130:131], v[162:163], v[186:187]
	v_pk_fma_f32 v[190:191], v[146:147], v[174:175], v[190:191]
	v_pk_add_f32 v[184:185], v[184:185], v[132:133]
	v_pk_add_f32 v[188:189], v[188:189], v[148:149]
	v_pk_add_f32 v[186:187], v[186:187], v[134:135]
	v_pk_add_f32 v[190:191], v[190:191], v[150:151]
	v_mul_f32_e32 v192, 0xbfb8aa3b, v188
	v_mul_f32_e32 v193, 0xbfb8aa3b, v189
	v_mul_f32_e32 v194, 0xbfb8aa3b, v190
	v_mul_f32_e32 v195, 0xbfb8aa3b, v191
	v_exp_f32_e32 v192, v192
	v_exp_f32_e32 v193, v193
	v_exp_f32_e32 v194, v194
	v_exp_f32_e32 v195, v195
	s_nop 0
	v_pk_add_f32 v[192:193], v[192:193], 1.0 op_sel_hi:[1,0]
	v_pk_add_f32 v[194:195], v[194:195], 1.0 op_sel_hi:[1,0]
	v_div_scale_f32 v224, s[8:9], v192, v192, 1.0
	v_div_scale_f32 v229, s[8:9], v193, v193, 1.0
	v_div_scale_f32 v234, s[8:9], v194, v194, 1.0
	v_div_scale_f32 v239, s[8:9], v195, v195, 1.0
	v_div_scale_f32 v225, s[20:21], 1.0, v192, 1.0
	v_div_scale_f32 v230, s[22:23], 1.0, v193, 1.0
	v_div_scale_f32 v235, s[24:25], 1.0, v194, 1.0
	v_div_scale_f32 v240, s[26:27], 1.0, v195, 1.0
	v_rcp_f32_e32 v226, v224
	v_rcp_f32_e32 v231, v229
	v_rcp_f32_e32 v236, v234
	v_rcp_f32_e32 v241, v239
	v_fma_f32 v228, -v224, v226, 1.0
	v_fma_f32 v233, -v229, v231, 1.0
	v_fma_f32 v238, -v234, v236, 1.0
	v_fma_f32 v243, -v239, v241, 1.0
	v_fmac_f32_e32 v226, v228, v226
	v_fmac_f32_e32 v231, v233, v231
	v_fmac_f32_e32 v236, v238, v236
	v_fmac_f32_e32 v241, v243, v241
	v_mul_f32_e32 v227, v225, v226
	v_mul_f32_e32 v232, v230, v231
	v_mul_f32_e32 v237, v235, v236
	v_mul_f32_e32 v242, v240, v241
	v_fma_f32 v228, -v224, v227, v225
	v_fma_f32 v233, -v229, v232, v230
	v_fma_f32 v238, -v234, v237, v235
	v_fma_f32 v243, -v239, v242, v240
	v_fmac_f32_e32 v227, v228, v226
	v_fmac_f32_e32 v232, v233, v231
	v_fmac_f32_e32 v237, v238, v236
	v_fmac_f32_e32 v242, v243, v241
	v_fma_f32 v228, -v224, v227, v225
	v_fma_f32 v233, -v229, v232, v230
	v_fma_f32 v238, -v234, v237, v235
	v_fma_f32 v243, -v239, v242, v240
	s_mov_b64 vcc, s[20:21]
	s_nop 0
	v_div_fmas_f32 v228, v228, v226, v227
	s_mov_b64 vcc, s[22:23]
	s_nop 0
	v_div_fmas_f32 v233, v233, v231, v232
	s_mov_b64 vcc, s[24:25]
	s_nop 0
	v_div_fmas_f32 v238, v238, v236, v237
	s_mov_b64 vcc, s[26:27]
	s_nop 0
	v_div_fmas_f32 v243, v243, v241, v242
	v_div_fixup_f32 v196, v228, v192, 1.0
	v_div_fixup_f32 v197, v233, v193, 1.0
	v_div_fixup_f32 v198, v238, v194, 1.0
	v_div_fixup_f32 v199, v243, v195, 1.0
	v_pk_mul_f32 v[196:197], v[188:189], v[196:197]
	v_pk_mul_f32 v[198:199], v[190:191], v[198:199]
	v_pk_mul_f32 v[196:197], v[184:185], v[196:197]
	v_pk_mul_f32 v[198:199], v[186:187], v[198:199]
	v_cvt_pk_bf16_f32 v208, v196, v197
	v_cvt_pk_bf16_f32 v209, v198, v199
	v_add_u32_e32 v156, 0x2c00, v156
	global_store_dwordx2 v156, v[208:209], s[18:19]
	s_mov_b64 exec, s[38:39]
	s_mov_b32 s38, 0x2e8ba2e9
	s_mov_b32 s39, 0x160000
	s_cbranch_execz .Lcv_done
	s_branch .Lcv_loop
